# hand-written phase-0 core: block-level modulation GEMV with 8-way K split, wave-private 64x64 register transposes for the bf16 weight copies
# speedup vs baseline: 1.2422x; 1.0039x over previous
; __device__ __forceinline__ void mod_gemv_item(const Params& P, int item, float* sm) {
;   const int tid = VTID;
;   const int l = item / 96, jg = item % 96;
;   for (int idx = tid; idx < 5120; idx += VTHR) {
;     const int m = idx >> 10, k = idx & 1023;
;     const float v = (m < 4) ? P.c[m * 1024 + k] : P.c_ctx[k];
;     sm[idx] = v / (1.f + __expf(-v));
;   }
;   __syncthreads();
;   const int kq = tid >> 6, jj = tid & 63;
;   float a0 = 0, a1 = 0, a2 = 0, a3 = 0, a4 = 0;
;   const float* w = P.w_mod + ((long)l * 1024 + kq * 256) * 6144 + jg * 64 + jj;
;   const float* s = sm + kq * 256;
; #pragma unroll 8
;   for (int k = 0; k < 256; ++k) {
;     const float wv = w[(long)k * 6144];
;     a0 += s[k] * wv; a1 += s[1024 + k] * wv; a2 += s[2048 + k] * wv; a3 += s[3072 + k] * wv; a4 += s[4096 + k] * wv;
.LBB0_10:
	s_load_dwordx16 s[4:19], s[0:1], 0x0
	v_writelane_b32 v252, s34, 18
	v_lshrrev_b32_e32 v153, 8, v152
	s_nop 0
	v_writelane_b32 v252, s35, 19
	s_waitcnt lgkmcnt(0)
	v_writelane_b32 v252, s4, 20
	s_nop 1
	v_writelane_b32 v252, s5, 21
	v_writelane_b32 v252, s6, 22
	v_writelane_b32 v252, s7, 23
	v_writelane_b32 v252, s8, 24
	v_writelane_b32 v252, s9, 25
	v_writelane_b32 v252, s10, 26
	v_writelane_b32 v252, s11, 27
	v_writelane_b32 v252, s12, 28
	v_writelane_b32 v252, s13, 29
	v_writelane_b32 v252, s14, 30
	v_writelane_b32 v252, s15, 31
	v_writelane_b32 v252, s16, 32
	v_writelane_b32 v252, s17, 33
	v_writelane_b32 v252, s18, 34
	v_writelane_b32 v252, s19, 35
	s_load_dwordx16 s[4:19], s[0:1], 0x40
	s_waitcnt lgkmcnt(0)
	v_writelane_b32 v252, s4, 36
	s_nop 1
	v_writelane_b32 v252, s5, 37
	v_writelane_b32 v252, s6, 38
	v_writelane_b32 v252, s7, 39
	v_writelane_b32 v252, s8, 40
	v_writelane_b32 v252, s9, 41
	v_writelane_b32 v252, s10, 42
	v_writelane_b32 v252, s11, 43
	v_writelane_b32 v252, s12, 44
	v_writelane_b32 v252, s13, 45
	v_writelane_b32 v252, s14, 46
	v_writelane_b32 v252, s15, 47
	v_writelane_b32 v252, s16, 48
	v_writelane_b32 v252, s17, 49
	v_writelane_b32 v252, s18, 50
	v_writelane_b32 v252, s19, 51
	s_load_dwordx2 s[6:7], s[0:1], 0x168
	s_load_dwordx16 s[56:71], s[0:1], 0x80
	s_waitcnt lgkmcnt(0)
	s_barrier
	s_cmp_gt_i32 s6, 0
	s_cselect_b64 s[0:1], -1, 0
	s_cmp_lt_i32 s7, 1
	s_cselect_b64 s[4:5], -1, 0
	s_or_b64 s[0:1], s[0:1], s[4:5]
	s_and_b64 vcc, exec, s[0:1]
	s_cbranch_vccnz .LBB0_93
	v_mov_b32_e32 v1, v153
	s_mov_b32 s3, 0x12000
	v_lshl_add_u32 v28, s2, 1, v153
	v_mul_lo_u32 v12, v1, s3
	s_movk_i32 s0, 0xc0
	v_writelane_b32 v252, s6, 52
	v_add_u32_e32 v1, 16, v12
	v_cmp_gt_i32_e32 vcc, s0, v28
	v_writelane_b32 v252, s7, 53
	v_lshrrev_b32_e32 v1, 6, v152
	v_and_b32_e32 v3, 63, v152
	v_readlane_b32 s4, v252, 0
	v_readlane_b32 s5, v252, 1
	v_readfirstlane_b32 s3, v1
	v_lshlrev_b32_e32 v2, 2, v3
	s_sub_u32 s4, s4, 0x170
	s_subb_u32 s5, s5, 0
	s_cmp_lt_u32 s2, 192
	s_cbranch_scc0 .Lmy_p0_tr
	s_load_dwordx2 s[8:9], s[4:5], 0x8
	s_load_dwordx2 s[10:11], s[4:5], 0x18
	s_load_dwordx2 s[12:13], s[4:5], 0x20
	s_load_dwordx2 s[14:15], s[4:5], 0x28
	s_load_dwordx2 s[16:17], s[4:5], 0x100
	s_cmp_ge_u32 s2, 96
	s_cselect_b32 s18, 1, 0
	s_mul_i32 s19, s18, 96
	s_sub_u32 s19, s2, s19
	v_lshlrev_b32_e32 v4, 2, v152
	s_waitcnt lgkmcnt(0)
	s_add_u32 s20, s8, 0x0
	s_addc_u32 s21, s9, 0
	global_load_dword v64, v4, s[20:21] offset:0
	global_load_dword v65, v4, s[20:21] offset:2048
	s_add_u32 s20, s8, 0x1000
	s_addc_u32 s21, s9, 0
	global_load_dword v66, v4, s[20:21] offset:0
	global_load_dword v67, v4, s[20:21] offset:2048
	s_add_u32 s20, s8, 0x2000
	s_addc_u32 s21, s9, 0
	global_load_dword v68, v4, s[20:21] offset:0
	global_load_dword v69, v4, s[20:21] offset:2048
	s_add_u32 s20, s8, 0x3000
	s_addc_u32 s21, s9, 0
	global_load_dword v70, v4, s[20:21] offset:0
	global_load_dword v71, v4, s[20:21] offset:2048
	global_load_dword v72, v4, s[10:11] offset:0
	global_load_dword v73, v4, s[10:11] offset:2048
	s_lshl_b32 s20, s18, 10
	s_lshl_b32 s21, s3, 7
	s_add_u32 s20, s20, s21
	s_mul_i32 s20, s20, 0x6000
	s_lshl_b32 s21, s19, 8
	s_add_u32 s20, s20, s21
	s_add_u32 s22, s12, s20
	s_addc_u32 s23, s13, 0
	global_load_dword v96, v2, s[22:23]
	s_add_u32 s22, s22, 0x6000
	s_addc_u32 s23, s23, 0
	global_load_dword v97, v2, s[22:23]
	s_add_u32 s22, s22, 0x6000
	s_addc_u32 s23, s23, 0
	global_load_dword v98, v2, s[22:23]
	s_add_u32 s22, s22, 0x6000
	s_addc_u32 s23, s23, 0
	global_load_dword v99, v2, s[22:23]
	s_add_u32 s22, s22, 0x6000
	s_addc_u32 s23, s23, 0
	global_load_dword v100, v2, s[22:23]
	s_add_u32 s22, s22, 0x6000
	s_addc_u32 s23, s23, 0
	global_load_dword v101, v2, s[22:23]
	s_add_u32 s22, s22, 0x6000
	s_addc_u32 s23, s23, 0
	global_load_dword v102, v2, s[22:23]
	s_add_u32 s22, s22, 0x6000
	s_addc_u32 s23, s23, 0
	global_load_dword v103, v2, s[22:23]
	s_add_u32 s22, s22, 0x6000
	s_addc_u32 s23, s23, 0
	global_load_dword v104, v2, s[22:23]
	s_add_u32 s22, s22, 0x6000
	s_addc_u32 s23, s23, 0
	global_load_dword v105, v2, s[22:23]
	s_add_u32 s22, s22, 0x6000
	s_addc_u32 s23, s23, 0
	global_load_dword v106, v2, s[22:23]
	s_add_u32 s22, s22, 0x6000
	s_addc_u32 s23, s23, 0
	global_load_dword v107, v2, s[22:23]
	s_add_u32 s22, s22, 0x6000
	s_addc_u32 s23, s23, 0
	global_load_dword v108, v2, s[22:23]
	s_add_u32 s22, s22, 0x6000
	s_addc_u32 s23, s23, 0
	global_load_dword v109, v2, s[22:23]
	s_add_u32 s22, s22, 0x6000
	s_addc_u32 s23, s23, 0
	global_load_dword v110, v2, s[22:23]
	s_add_u32 s22, s22, 0x6000
	s_addc_u32 s23, s23, 0
	global_load_dword v111, v2, s[22:23]
	s_add_u32 s22, s22, 0x6000
	s_addc_u32 s23, s23, 0
	global_load_dword v112, v2, s[22:23]
	s_add_u32 s22, s22, 0x6000
	s_addc_u32 s23, s23, 0
	global_load_dword v113, v2, s[22:23]
	s_add_u32 s22, s22, 0x6000
	s_addc_u32 s23, s23, 0
	global_load_dword v114, v2, s[22:23]
	s_add_u32 s22, s22, 0x6000
	s_addc_u32 s23, s23, 0
	global_load_dword v115, v2, s[22:23]
	s_add_u32 s22, s22, 0x6000
	s_addc_u32 s23, s23, 0
	global_load_dword v116, v2, s[22:23]
	s_add_u32 s22, s22, 0x6000
	s_addc_u32 s23, s23, 0
	global_load_dword v117, v2, s[22:23]
	s_add_u32 s22, s22, 0x6000
	s_addc_u32 s23, s23, 0
	global_load_dword v118, v2, s[22:23]
	s_add_u32 s22, s22, 0x6000
	s_addc_u32 s23, s23, 0
	global_load_dword v119, v2, s[22:23]
	s_add_u32 s22, s22, 0x6000
	s_addc_u32 s23, s23, 0
	global_load_dword v120, v2, s[22:23]
	s_add_u32 s22, s22, 0x6000
	s_addc_u32 s23, s23, 0
	global_load_dword v121, v2, s[22:23]
	s_add_u32 s22, s22, 0x6000
	s_addc_u32 s23, s23, 0
	global_load_dword v122, v2, s[22:23]
; __device__ __forceinline__ void mod_gemv_item(const Params& P, int item, float* sm) {
;     ...
;   for (int idx = tid; idx < 5120; idx += VTHR) {
;     const int m = idx >> 10, k = idx & 1023;
;     const float v = (m < 4) ? P.c[m * 1024 + k] : P.c_ctx[k];
;     sm[idx] = v / (1.f + __expf(-v));
;   }
	s_add_u32 s22, s22, 0x6000
	s_addc_u32 s23, s23, 0
	global_load_dword v123, v2, s[22:23]
	s_add_u32 s22, s22, 0x6000
	s_addc_u32 s23, s23, 0
	global_load_dword v124, v2, s[22:23]
	s_add_u32 s22, s22, 0x6000
	s_addc_u32 s23, s23, 0
	global_load_dword v125, v2, s[22:23]
	s_add_u32 s22, s22, 0x6000
	s_addc_u32 s23, s23, 0
	global_load_dword v126, v2, s[22:23]
	s_add_u32 s22, s22, 0x6000
	s_addc_u32 s23, s23, 0
	global_load_dword v127, v2, s[22:23]
	s_add_u32 s22, s22, 0x6000
	s_addc_u32 s23, s23, 0
	global_load_dword v128, v2, s[22:23]
	s_add_u32 s22, s22, 0x6000
	s_addc_u32 s23, s23, 0
	global_load_dword v129, v2, s[22:23]
	s_add_u32 s22, s22, 0x6000
	s_addc_u32 s23, s23, 0
	global_load_dword v130, v2, s[22:23]
	s_add_u32 s22, s22, 0x6000
	s_addc_u32 s23, s23, 0
	global_load_dword v131, v2, s[22:23]
	s_add_u32 s22, s22, 0x6000
	s_addc_u32 s23, s23, 0
	global_load_dword v132, v2, s[22:23]
	s_add_u32 s22, s22, 0x6000
	s_addc_u32 s23, s23, 0
	global_load_dword v133, v2, s[22:23]
	s_add_u32 s22, s22, 0x6000
	s_addc_u32 s23, s23, 0
	global_load_dword v134, v2, s[22:23]
	s_add_u32 s22, s22, 0x6000
	s_addc_u32 s23, s23, 0
	global_load_dword v135, v2, s[22:23]
	s_add_u32 s22, s22, 0x6000
	s_addc_u32 s23, s23, 0
	global_load_dword v136, v2, s[22:23]
	s_add_u32 s22, s22, 0x6000
	s_addc_u32 s23, s23, 0
	global_load_dword v137, v2, s[22:23]
	s_add_u32 s22, s22, 0x6000
	s_addc_u32 s23, s23, 0
	global_load_dword v138, v2, s[22:23]
	s_add_u32 s22, s22, 0x6000
	s_addc_u32 s23, s23, 0
	global_load_dword v139, v2, s[22:23]
	s_add_u32 s22, s22, 0x6000
	s_addc_u32 s23, s23, 0
	global_load_dword v140, v2, s[22:23]
	s_add_u32 s22, s22, 0x6000
	s_addc_u32 s23, s23, 0
	global_load_dword v141, v2, s[22:23]
	s_add_u32 s22, s22, 0x6000
	s_addc_u32 s23, s23, 0
	global_load_dword v142, v2, s[22:23]
	s_add_u32 s22, s22, 0x6000
	s_addc_u32 s23, s23, 0
	global_load_dword v143, v2, s[22:23]
	s_add_u32 s22, s22, 0x6000
	s_addc_u32 s23, s23, 0
	s_waitcnt vmcnt(48)
	v_mul_f32_e32 v20, 0xbfb8aa3b, v64
	v_exp_f32_e32 v20, v20
	s_nop 0
	v_add_f32_e32 v20, 1.0, v20
	v_div_scale_f32 v21, s[24:25], v20, v20, v64
	v_rcp_f32_e32 v22, v21
	v_div_scale_f32 v23, vcc, v64, v20, v64
	v_fma_f32 v24, -v21, v22, 1.0
	v_fmac_f32_e32 v22, v24, v22
	v_mul_f32_e32 v24, v23, v22
	v_fma_f32 v25, -v21, v24, v23
	v_fmac_f32_e32 v24, v25, v22
	v_fma_f32 v21, -v21, v24, v23
	v_div_fmas_f32 v21, v21, v22, v24
	v_div_fixup_f32 v64, v21, v20, v64
	ds_write_b32 v4, v64 offset:16
	v_mul_f32_e32 v20, 0xbfb8aa3b, v65
	v_exp_f32_e32 v20, v20
	s_nop 0
	v_add_f32_e32 v20, 1.0, v20
	v_div_scale_f32 v21, s[24:25], v20, v20, v65
	v_rcp_f32_e32 v22, v21
	v_div_scale_f32 v23, vcc, v65, v20, v65
	v_fma_f32 v24, -v21, v22, 1.0
	v_fmac_f32_e32 v22, v24, v22
	v_mul_f32_e32 v24, v23, v22
	v_fma_f32 v25, -v21, v24, v23
	v_fmac_f32_e32 v24, v25, v22
	v_fma_f32 v21, -v21, v24, v23
	v_div_fmas_f32 v21, v21, v22, v24
	v_div_fixup_f32 v65, v21, v20, v65
	ds_write_b32 v4, v65 offset:2064
	v_mul_f32_e32 v20, 0xbfb8aa3b, v66
	v_exp_f32_e32 v20, v20
	s_nop 0
	v_add_f32_e32 v20, 1.0, v20
	v_div_scale_f32 v21, s[24:25], v20, v20, v66
	v_rcp_f32_e32 v22, v21
	v_div_scale_f32 v23, vcc, v66, v20, v66
	v_fma_f32 v24, -v21, v22, 1.0
	v_fmac_f32_e32 v22, v24, v22
	v_mul_f32_e32 v24, v23, v22
	v_fma_f32 v25, -v21, v24, v23
	v_fmac_f32_e32 v24, v25, v22
	v_fma_f32 v21, -v21, v24, v23
	v_div_fmas_f32 v21, v21, v22, v24
	v_div_fixup_f32 v66, v21, v20, v66
	ds_write_b32 v4, v66 offset:4112
	v_mul_f32_e32 v20, 0xbfb8aa3b, v67
	v_exp_f32_e32 v20, v20
	s_nop 0
	v_add_f32_e32 v20, 1.0, v20
	v_div_scale_f32 v21, s[24:25], v20, v20, v67
	v_rcp_f32_e32 v22, v21
	v_div_scale_f32 v23, vcc, v67, v20, v67
	v_fma_f32 v24, -v21, v22, 1.0
	v_fmac_f32_e32 v22, v24, v22
	v_mul_f32_e32 v24, v23, v22
	v_fma_f32 v25, -v21, v24, v23
	v_fmac_f32_e32 v24, v25, v22
	v_fma_f32 v21, -v21, v24, v23
	v_div_fmas_f32 v21, v21, v22, v24
	v_div_fixup_f32 v67, v21, v20, v67
	ds_write_b32 v4, v67 offset:6160
	v_mul_f32_e32 v20, 0xbfb8aa3b, v68
	v_exp_f32_e32 v20, v20
	s_nop 0
	v_add_f32_e32 v20, 1.0, v20
	v_div_scale_f32 v21, s[24:25], v20, v20, v68
	v_rcp_f32_e32 v22, v21
	v_div_scale_f32 v23, vcc, v68, v20, v68
	v_fma_f32 v24, -v21, v22, 1.0
	v_fmac_f32_e32 v22, v24, v22
	v_mul_f32_e32 v24, v23, v22
	v_fma_f32 v25, -v21, v24, v23
	v_fmac_f32_e32 v24, v25, v22
	v_fma_f32 v21, -v21, v24, v23
	v_div_fmas_f32 v21, v21, v22, v24
	v_div_fixup_f32 v68, v21, v20, v68
	ds_write_b32 v4, v68 offset:8208
	v_mul_f32_e32 v20, 0xbfb8aa3b, v69
	v_exp_f32_e32 v20, v20
	s_nop 0
	v_add_f32_e32 v20, 1.0, v20
	v_div_scale_f32 v21, s[24:25], v20, v20, v69
	v_rcp_f32_e32 v22, v21
	v_div_scale_f32 v23, vcc, v69, v20, v69
	v_fma_f32 v24, -v21, v22, 1.0
	v_fmac_f32_e32 v22, v24, v22
	v_mul_f32_e32 v24, v23, v22
	v_fma_f32 v25, -v21, v24, v23
	v_fmac_f32_e32 v24, v25, v22
	v_fma_f32 v21, -v21, v24, v23
	v_div_fmas_f32 v21, v21, v22, v24
	v_div_fixup_f32 v69, v21, v20, v69
	ds_write_b32 v4, v69 offset:10256
	v_mul_f32_e32 v20, 0xbfb8aa3b, v70
	v_exp_f32_e32 v20, v20
	s_nop 0
	v_add_f32_e32 v20, 1.0, v20
	v_div_scale_f32 v21, s[24:25], v20, v20, v70
	v_rcp_f32_e32 v22, v21
	v_div_scale_f32 v23, vcc, v70, v20, v70
	v_fma_f32 v24, -v21, v22, 1.0
	v_fmac_f32_e32 v22, v24, v22
	v_mul_f32_e32 v24, v23, v22
	v_fma_f32 v25, -v21, v24, v23
	v_fmac_f32_e32 v24, v25, v22
	v_fma_f32 v21, -v21, v24, v23
	v_div_fmas_f32 v21, v21, v22, v24
	v_div_fixup_f32 v70, v21, v20, v70
	ds_write_b32 v4, v70 offset:12304
	v_mul_f32_e32 v20, 0xbfb8aa3b, v71
	v_exp_f32_e32 v20, v20
	s_nop 0
	v_add_f32_e32 v20, 1.0, v20
	v_div_scale_f32 v21, s[24:25], v20, v20, v71
	v_rcp_f32_e32 v22, v21
	v_div_scale_f32 v23, vcc, v71, v20, v71
; __device__ __forceinline__ void mod_gemv_item(const Params& P, int item, float* sm) {
;     ...
;   for (int idx = tid; idx < 5120; idx += VTHR) {
;     const int m = idx >> 10, k = idx & 1023;
;     const float v = (m < 4) ? P.c[m * 1024 + k] : P.c_ctx[k];
;     sm[idx] = v / (1.f + __expf(-v));
;   }
;   __syncthreads();
;   const int kq = tid >> 6, jj = tid & 63;
;   float a0 = 0, a1 = 0, a2 = 0, a3 = 0, a4 = 0;
;   const float* w = P.w_mod + ((long)l * 1024 + kq * 256) * 6144 + jg * 64 + jj;
;   const float* s = sm + kq * 256;
; #pragma unroll 8
;   for (int k = 0; k < 256; ++k) {
;     const float wv = w[(long)k * 6144];
;     a0 += s[k] * wv; a1 += s[1024 + k] * wv; a2 += s[2048 + k] * wv; a3 += s[3072 + k] * wv; a4 += s[4096 + k] * wv;
;   }
	v_fma_f32 v24, -v21, v22, 1.0
	v_fmac_f32_e32 v22, v24, v22
	v_mul_f32_e32 v24, v23, v22
	v_fma_f32 v25, -v21, v24, v23
	v_fmac_f32_e32 v24, v25, v22
	v_fma_f32 v21, -v21, v24, v23
	v_div_fmas_f32 v21, v21, v22, v24
	v_div_fixup_f32 v71, v21, v20, v71
	ds_write_b32 v4, v71 offset:14352
	v_mul_f32_e32 v20, 0xbfb8aa3b, v72
	v_exp_f32_e32 v20, v20
	s_nop 0
	v_add_f32_e32 v20, 1.0, v20
	v_div_scale_f32 v21, s[24:25], v20, v20, v72
	v_rcp_f32_e32 v22, v21
	v_div_scale_f32 v23, vcc, v72, v20, v72
	v_fma_f32 v24, -v21, v22, 1.0
	v_fmac_f32_e32 v22, v24, v22
	v_mul_f32_e32 v24, v23, v22
	v_fma_f32 v25, -v21, v24, v23
	v_fmac_f32_e32 v24, v25, v22
	v_fma_f32 v21, -v21, v24, v23
	v_div_fmas_f32 v21, v21, v22, v24
	v_div_fixup_f32 v72, v21, v20, v72
	ds_write_b32 v4, v72 offset:16400
	v_mul_f32_e32 v20, 0xbfb8aa3b, v73
	v_exp_f32_e32 v20, v20
	s_nop 0
	v_add_f32_e32 v20, 1.0, v20
	v_div_scale_f32 v21, s[24:25], v20, v20, v73
	v_rcp_f32_e32 v22, v21
	v_div_scale_f32 v23, vcc, v73, v20, v73
	v_fma_f32 v24, -v21, v22, 1.0
	v_fmac_f32_e32 v22, v24, v22
	v_mul_f32_e32 v24, v23, v22
	v_fma_f32 v25, -v21, v24, v23
	v_fmac_f32_e32 v24, v25, v22
	v_fma_f32 v21, -v21, v24, v23
	v_div_fmas_f32 v21, v21, v22, v24
	v_div_fixup_f32 v73, v21, v20, v73
	ds_write_b32 v4, v73 offset:18448
	v_mov_b32_e32 v5, 0x10
	v_lshl_add_u32 v5, s3, 9, v5
	v_mov_b32_e32 v30, 0
	v_mov_b32_e32 v31, 0
	v_mov_b32_e32 v32, 0
	v_mov_b32_e32 v33, 0
	v_mov_b32_e32 v34, 0
	s_waitcnt lgkmcnt(0)
	s_barrier
	s_waitcnt vmcnt(32)
	ds_read_b128 v[36:39], v5 offset:0
	ds_read_b128 v[40:43], v5 offset:4096
	ds_read_b128 v[44:47], v5 offset:8192
	ds_read_b128 v[48:51], v5 offset:12288
	ds_read_b128 v[52:55], v5 offset:16384
	s_waitcnt lgkmcnt(4)
	v_fmac_f32_e32 v30, v36, v96
	s_waitcnt lgkmcnt(3)
	v_fmac_f32_e32 v31, v40, v96
	s_waitcnt lgkmcnt(2)
	v_fmac_f32_e32 v32, v44, v96
	s_waitcnt lgkmcnt(1)
	v_fmac_f32_e32 v33, v48, v96
	s_waitcnt lgkmcnt(0)
	v_fmac_f32_e32 v34, v52, v96
	v_fmac_f32_e32 v30, v37, v97
	v_fmac_f32_e32 v31, v41, v97
	v_fmac_f32_e32 v32, v45, v97
	v_fmac_f32_e32 v33, v49, v97
	v_fmac_f32_e32 v34, v53, v97
	v_fmac_f32_e32 v30, v38, v98
	v_fmac_f32_e32 v31, v42, v98
	v_fmac_f32_e32 v32, v46, v98
	v_fmac_f32_e32 v33, v50, v98
	v_fmac_f32_e32 v34, v54, v98
	v_fmac_f32_e32 v30, v39, v99
	v_fmac_f32_e32 v31, v43, v99
	v_fmac_f32_e32 v32, v47, v99
	v_fmac_f32_e32 v33, v51, v99
	v_fmac_f32_e32 v34, v55, v99
	ds_read_b128 v[36:39], v5 offset:16
	ds_read_b128 v[40:43], v5 offset:4112
	ds_read_b128 v[44:47], v5 offset:8208
	ds_read_b128 v[48:51], v5 offset:12304
	ds_read_b128 v[52:55], v5 offset:16400
	s_waitcnt lgkmcnt(4)
	v_fmac_f32_e32 v30, v36, v100
	s_waitcnt lgkmcnt(3)
	v_fmac_f32_e32 v31, v40, v100
	s_waitcnt lgkmcnt(2)
	v_fmac_f32_e32 v32, v44, v100
	s_waitcnt lgkmcnt(1)
	v_fmac_f32_e32 v33, v48, v100
	s_waitcnt lgkmcnt(0)
	v_fmac_f32_e32 v34, v52, v100
	v_fmac_f32_e32 v30, v37, v101
	v_fmac_f32_e32 v31, v41, v101
	v_fmac_f32_e32 v32, v45, v101
	v_fmac_f32_e32 v33, v49, v101
	v_fmac_f32_e32 v34, v53, v101
	v_fmac_f32_e32 v30, v38, v102
	v_fmac_f32_e32 v31, v42, v102
	v_fmac_f32_e32 v32, v46, v102
	v_fmac_f32_e32 v33, v50, v102
	v_fmac_f32_e32 v34, v54, v102
	v_fmac_f32_e32 v30, v39, v103
	v_fmac_f32_e32 v31, v43, v103
	v_fmac_f32_e32 v32, v47, v103
	v_fmac_f32_e32 v33, v51, v103
	v_fmac_f32_e32 v34, v55, v103
	ds_read_b128 v[36:39], v5 offset:32
	ds_read_b128 v[40:43], v5 offset:4128
	ds_read_b128 v[44:47], v5 offset:8224
	ds_read_b128 v[48:51], v5 offset:12320
	ds_read_b128 v[52:55], v5 offset:16416
	s_waitcnt lgkmcnt(4)
	v_fmac_f32_e32 v30, v36, v104
	s_waitcnt lgkmcnt(3)
	v_fmac_f32_e32 v31, v40, v104
	s_waitcnt lgkmcnt(2)
	v_fmac_f32_e32 v32, v44, v104
	s_waitcnt lgkmcnt(1)
	v_fmac_f32_e32 v33, v48, v104
	s_waitcnt lgkmcnt(0)
	v_fmac_f32_e32 v34, v52, v104
	v_fmac_f32_e32 v30, v37, v105
	v_fmac_f32_e32 v31, v41, v105
	v_fmac_f32_e32 v32, v45, v105
	v_fmac_f32_e32 v33, v49, v105
	v_fmac_f32_e32 v34, v53, v105
	v_fmac_f32_e32 v30, v38, v106
	v_fmac_f32_e32 v31, v42, v106
	v_fmac_f32_e32 v32, v46, v106
	v_fmac_f32_e32 v33, v50, v106
	v_fmac_f32_e32 v34, v54, v106
	v_fmac_f32_e32 v30, v39, v107
	v_fmac_f32_e32 v31, v43, v107
	v_fmac_f32_e32 v32, v47, v107
	v_fmac_f32_e32 v33, v51, v107
	v_fmac_f32_e32 v34, v55, v107
	ds_read_b128 v[36:39], v5 offset:48
	ds_read_b128 v[40:43], v5 offset:4144
	ds_read_b128 v[44:47], v5 offset:8240
	ds_read_b128 v[48:51], v5 offset:12336
	ds_read_b128 v[52:55], v5 offset:16432
	s_waitcnt lgkmcnt(4)
	v_fmac_f32_e32 v30, v36, v108
	s_waitcnt lgkmcnt(3)
	v_fmac_f32_e32 v31, v40, v108
	s_waitcnt lgkmcnt(2)
	v_fmac_f32_e32 v32, v44, v108
	s_waitcnt lgkmcnt(1)
	v_fmac_f32_e32 v33, v48, v108
	s_waitcnt lgkmcnt(0)
; __device__ __forceinline__ void mod_gemv_item(const Params& P, int item, float* sm) {
;     ...
;   const int kq = tid >> 6, jj = tid & 63;
;   float a0 = 0, a1 = 0, a2 = 0, a3 = 0, a4 = 0;
;   const float* w = P.w_mod + ((long)l * 1024 + kq * 256) * 6144 + jg * 64 + jj;
;   const float* s = sm + kq * 256;
; #pragma unroll 8
;   for (int k = 0; k < 256; ++k) {
;     const float wv = w[(long)k * 6144];
;     a0 += s[k] * wv; a1 += s[1024 + k] * wv; a2 += s[2048 + k] * wv; a3 += s[3072 + k] * wv; a4 += s[4096 + k] * wv;
;   }
	v_fmac_f32_e32 v34, v52, v108
	v_fmac_f32_e32 v30, v37, v109
	v_fmac_f32_e32 v31, v41, v109
	v_fmac_f32_e32 v32, v45, v109
	v_fmac_f32_e32 v33, v49, v109
	v_fmac_f32_e32 v34, v53, v109
	v_fmac_f32_e32 v30, v38, v110
	v_fmac_f32_e32 v31, v42, v110
	v_fmac_f32_e32 v32, v46, v110
	v_fmac_f32_e32 v33, v50, v110
	v_fmac_f32_e32 v34, v54, v110
	v_fmac_f32_e32 v30, v39, v111
	v_fmac_f32_e32 v31, v43, v111
	v_fmac_f32_e32 v32, v47, v111
	v_fmac_f32_e32 v33, v51, v111
	v_fmac_f32_e32 v34, v55, v111
	global_load_dword v160, v2, s[22:23]
	s_add_u32 s22, s22, 0x6000
	s_addc_u32 s23, s23, 0
	global_load_dword v161, v2, s[22:23]
	s_add_u32 s22, s22, 0x6000
	s_addc_u32 s23, s23, 0
	global_load_dword v162, v2, s[22:23]
	s_add_u32 s22, s22, 0x6000
	s_addc_u32 s23, s23, 0
	global_load_dword v163, v2, s[22:23]
	s_add_u32 s22, s22, 0x6000
	s_addc_u32 s23, s23, 0
	global_load_dword v164, v2, s[22:23]
	s_add_u32 s22, s22, 0x6000
	s_addc_u32 s23, s23, 0
	global_load_dword v165, v2, s[22:23]
	s_add_u32 s22, s22, 0x6000
	s_addc_u32 s23, s23, 0
	global_load_dword v166, v2, s[22:23]
	s_add_u32 s22, s22, 0x6000
	s_addc_u32 s23, s23, 0
	global_load_dword v167, v2, s[22:23]
	s_add_u32 s22, s22, 0x6000
	s_addc_u32 s23, s23, 0
	global_load_dword v168, v2, s[22:23]
	s_add_u32 s22, s22, 0x6000
	s_addc_u32 s23, s23, 0
	global_load_dword v169, v2, s[22:23]
	s_add_u32 s22, s22, 0x6000
	s_addc_u32 s23, s23, 0
	global_load_dword v170, v2, s[22:23]
	s_add_u32 s22, s22, 0x6000
	s_addc_u32 s23, s23, 0
	global_load_dword v171, v2, s[22:23]
	s_add_u32 s22, s22, 0x6000
	s_addc_u32 s23, s23, 0
	global_load_dword v172, v2, s[22:23]
	s_add_u32 s22, s22, 0x6000
	s_addc_u32 s23, s23, 0
	global_load_dword v173, v2, s[22:23]
	s_add_u32 s22, s22, 0x6000
	s_addc_u32 s23, s23, 0
	global_load_dword v174, v2, s[22:23]
	s_add_u32 s22, s22, 0x6000
	s_addc_u32 s23, s23, 0
	global_load_dword v175, v2, s[22:23]
	s_add_u32 s22, s22, 0x6000
	s_addc_u32 s23, s23, 0
	s_waitcnt vmcnt(32)
	ds_read_b128 v[36:39], v5 offset:64
	ds_read_b128 v[40:43], v5 offset:4160
	ds_read_b128 v[44:47], v5 offset:8256
	ds_read_b128 v[48:51], v5 offset:12352
	ds_read_b128 v[52:55], v5 offset:16448
	s_waitcnt lgkmcnt(4)
	v_fmac_f32_e32 v30, v36, v112
	s_waitcnt lgkmcnt(3)
	v_fmac_f32_e32 v31, v40, v112
	s_waitcnt lgkmcnt(2)
	v_fmac_f32_e32 v32, v44, v112
	s_waitcnt lgkmcnt(1)
	v_fmac_f32_e32 v33, v48, v112
	s_waitcnt lgkmcnt(0)
	v_fmac_f32_e32 v34, v52, v112
	v_fmac_f32_e32 v30, v37, v113
	v_fmac_f32_e32 v31, v41, v113
	v_fmac_f32_e32 v32, v45, v113
	v_fmac_f32_e32 v33, v49, v113
	v_fmac_f32_e32 v34, v53, v113
	v_fmac_f32_e32 v30, v38, v114
	v_fmac_f32_e32 v31, v42, v114
	v_fmac_f32_e32 v32, v46, v114
	v_fmac_f32_e32 v33, v50, v114
	v_fmac_f32_e32 v34, v54, v114
	v_fmac_f32_e32 v30, v39, v115
	v_fmac_f32_e32 v31, v43, v115
	v_fmac_f32_e32 v32, v47, v115
	v_fmac_f32_e32 v33, v51, v115
	v_fmac_f32_e32 v34, v55, v115
	ds_read_b128 v[36:39], v5 offset:80
	ds_read_b128 v[40:43], v5 offset:4176
	ds_read_b128 v[44:47], v5 offset:8272
	ds_read_b128 v[48:51], v5 offset:12368
	ds_read_b128 v[52:55], v5 offset:16464
	s_waitcnt lgkmcnt(4)
	v_fmac_f32_e32 v30, v36, v116
	s_waitcnt lgkmcnt(3)
	v_fmac_f32_e32 v31, v40, v116
	s_waitcnt lgkmcnt(2)
	v_fmac_f32_e32 v32, v44, v116
	s_waitcnt lgkmcnt(1)
	v_fmac_f32_e32 v33, v48, v116
	s_waitcnt lgkmcnt(0)
	v_fmac_f32_e32 v34, v52, v116
	v_fmac_f32_e32 v30, v37, v117
	v_fmac_f32_e32 v31, v41, v117
	v_fmac_f32_e32 v32, v45, v117
	v_fmac_f32_e32 v33, v49, v117
	v_fmac_f32_e32 v34, v53, v117
	v_fmac_f32_e32 v30, v38, v118
	v_fmac_f32_e32 v31, v42, v118
	v_fmac_f32_e32 v32, v46, v118
	v_fmac_f32_e32 v33, v50, v118
	v_fmac_f32_e32 v34, v54, v118
	v_fmac_f32_e32 v30, v39, v119
	v_fmac_f32_e32 v31, v43, v119
	v_fmac_f32_e32 v32, v47, v119
	v_fmac_f32_e32 v33, v51, v119
	v_fmac_f32_e32 v34, v55, v119
	ds_read_b128 v[36:39], v5 offset:96
	ds_read_b128 v[40:43], v5 offset:4192
	ds_read_b128 v[44:47], v5 offset:8288
	ds_read_b128 v[48:51], v5 offset:12384
	ds_read_b128 v[52:55], v5 offset:16480
	s_waitcnt lgkmcnt(4)
	v_fmac_f32_e32 v30, v36, v120
	s_waitcnt lgkmcnt(3)
	v_fmac_f32_e32 v31, v40, v120
	s_waitcnt lgkmcnt(2)
	v_fmac_f32_e32 v32, v44, v120
	s_waitcnt lgkmcnt(1)
	v_fmac_f32_e32 v33, v48, v120
	s_waitcnt lgkmcnt(0)
	v_fmac_f32_e32 v34, v52, v120
	v_fmac_f32_e32 v30, v37, v121
	v_fmac_f32_e32 v31, v41, v121
	v_fmac_f32_e32 v32, v45, v121
	v_fmac_f32_e32 v33, v49, v121
	v_fmac_f32_e32 v34, v53, v121
	v_fmac_f32_e32 v30, v38, v122
	v_fmac_f32_e32 v31, v42, v122
	v_fmac_f32_e32 v32, v46, v122
	v_fmac_f32_e32 v33, v50, v122
	v_fmac_f32_e32 v34, v54, v122
	v_fmac_f32_e32 v30, v39, v123
	v_fmac_f32_e32 v31, v43, v123
	v_fmac_f32_e32 v32, v47, v123
	v_fmac_f32_e32 v33, v51, v123
	v_fmac_f32_e32 v34, v55, v123
	ds_read_b128 v[36:39], v5 offset:112
	ds_read_b128 v[40:43], v5 offset:4208
	ds_read_b128 v[44:47], v5 offset:8304
	ds_read_b128 v[48:51], v5 offset:12400
	ds_read_b128 v[52:55], v5 offset:16496
	s_waitcnt lgkmcnt(4)
	v_fmac_f32_e32 v30, v36, v124
	s_waitcnt lgkmcnt(3)
	v_fmac_f32_e32 v31, v40, v124
	s_waitcnt lgkmcnt(2)
	v_fmac_f32_e32 v32, v44, v124
	s_waitcnt lgkmcnt(1)
	v_fmac_f32_e32 v33, v48, v124
	s_waitcnt lgkmcnt(0)
; __device__ __forceinline__ void mod_gemv_item(const Params& P, int item, float* sm) {
;     ...
;   const int kq = tid >> 6, jj = tid & 63;
;   float a0 = 0, a1 = 0, a2 = 0, a3 = 0, a4 = 0;
;   const float* w = P.w_mod + ((long)l * 1024 + kq * 256) * 6144 + jg * 64 + jj;
;   const float* s = sm + kq * 256;
; #pragma unroll 8
;   for (int k = 0; k < 256; ++k) {
;     const float wv = w[(long)k * 6144];
;     a0 += s[k] * wv; a1 += s[1024 + k] * wv; a2 += s[2048 + k] * wv; a3 += s[3072 + k] * wv; a4 += s[4096 + k] * wv;
;   }
	v_fmac_f32_e32 v34, v52, v124
	v_fmac_f32_e32 v30, v37, v125
	v_fmac_f32_e32 v31, v41, v125
	v_fmac_f32_e32 v32, v45, v125
	v_fmac_f32_e32 v33, v49, v125
	v_fmac_f32_e32 v34, v53, v125
	v_fmac_f32_e32 v30, v38, v126
	v_fmac_f32_e32 v31, v42, v126
	v_fmac_f32_e32 v32, v46, v126
	v_fmac_f32_e32 v33, v50, v126
	v_fmac_f32_e32 v34, v54, v126
	v_fmac_f32_e32 v30, v39, v127
	v_fmac_f32_e32 v31, v43, v127
	v_fmac_f32_e32 v32, v47, v127
	v_fmac_f32_e32 v33, v51, v127
	v_fmac_f32_e32 v34, v55, v127
	global_load_dword v96, v2, s[22:23]
	s_add_u32 s22, s22, 0x6000
	s_addc_u32 s23, s23, 0
	global_load_dword v97, v2, s[22:23]
	s_add_u32 s22, s22, 0x6000
	s_addc_u32 s23, s23, 0
	global_load_dword v98, v2, s[22:23]
	s_add_u32 s22, s22, 0x6000
	s_addc_u32 s23, s23, 0
	global_load_dword v99, v2, s[22:23]
	s_add_u32 s22, s22, 0x6000
	s_addc_u32 s23, s23, 0
	global_load_dword v100, v2, s[22:23]
	s_add_u32 s22, s22, 0x6000
	s_addc_u32 s23, s23, 0
	global_load_dword v101, v2, s[22:23]
	s_add_u32 s22, s22, 0x6000
	s_addc_u32 s23, s23, 0
	global_load_dword v102, v2, s[22:23]
	s_add_u32 s22, s22, 0x6000
	s_addc_u32 s23, s23, 0
	global_load_dword v103, v2, s[22:23]
	s_add_u32 s22, s22, 0x6000
	s_addc_u32 s23, s23, 0
	global_load_dword v104, v2, s[22:23]
	s_add_u32 s22, s22, 0x6000
	s_addc_u32 s23, s23, 0
	global_load_dword v105, v2, s[22:23]
	s_add_u32 s22, s22, 0x6000
	s_addc_u32 s23, s23, 0
	global_load_dword v106, v2, s[22:23]
	s_add_u32 s22, s22, 0x6000
	s_addc_u32 s23, s23, 0
	global_load_dword v107, v2, s[22:23]
	s_add_u32 s22, s22, 0x6000
	s_addc_u32 s23, s23, 0
	global_load_dword v108, v2, s[22:23]
	s_add_u32 s22, s22, 0x6000
	s_addc_u32 s23, s23, 0
	global_load_dword v109, v2, s[22:23]
	s_add_u32 s22, s22, 0x6000
	s_addc_u32 s23, s23, 0
	global_load_dword v110, v2, s[22:23]
	s_add_u32 s22, s22, 0x6000
	s_addc_u32 s23, s23, 0
	global_load_dword v111, v2, s[22:23]
	s_add_u32 s22, s22, 0x6000
	s_addc_u32 s23, s23, 0
	s_waitcnt vmcnt(32)
	ds_read_b128 v[36:39], v5 offset:128
	ds_read_b128 v[40:43], v5 offset:4224
	ds_read_b128 v[44:47], v5 offset:8320
	ds_read_b128 v[48:51], v5 offset:12416
	ds_read_b128 v[52:55], v5 offset:16512
	s_waitcnt lgkmcnt(4)
	v_fmac_f32_e32 v30, v36, v128
	s_waitcnt lgkmcnt(3)
	v_fmac_f32_e32 v31, v40, v128
	s_waitcnt lgkmcnt(2)
	v_fmac_f32_e32 v32, v44, v128
	s_waitcnt lgkmcnt(1)
	v_fmac_f32_e32 v33, v48, v128
	s_waitcnt lgkmcnt(0)
	v_fmac_f32_e32 v34, v52, v128
	v_fmac_f32_e32 v30, v37, v129
	v_fmac_f32_e32 v31, v41, v129
	v_fmac_f32_e32 v32, v45, v129
	v_fmac_f32_e32 v33, v49, v129
	v_fmac_f32_e32 v34, v53, v129
	v_fmac_f32_e32 v30, v38, v130
	v_fmac_f32_e32 v31, v42, v130
	v_fmac_f32_e32 v32, v46, v130
	v_fmac_f32_e32 v33, v50, v130
	v_fmac_f32_e32 v34, v54, v130
	v_fmac_f32_e32 v30, v39, v131
	v_fmac_f32_e32 v31, v43, v131
	v_fmac_f32_e32 v32, v47, v131
	v_fmac_f32_e32 v33, v51, v131
	v_fmac_f32_e32 v34, v55, v131
	ds_read_b128 v[36:39], v5 offset:144
	ds_read_b128 v[40:43], v5 offset:4240
	ds_read_b128 v[44:47], v5 offset:8336
	ds_read_b128 v[48:51], v5 offset:12432
	ds_read_b128 v[52:55], v5 offset:16528
	s_waitcnt lgkmcnt(4)
	v_fmac_f32_e32 v30, v36, v132
	s_waitcnt lgkmcnt(3)
	v_fmac_f32_e32 v31, v40, v132
	s_waitcnt lgkmcnt(2)
	v_fmac_f32_e32 v32, v44, v132
	s_waitcnt lgkmcnt(1)
	v_fmac_f32_e32 v33, v48, v132
	s_waitcnt lgkmcnt(0)
	v_fmac_f32_e32 v34, v52, v132
	v_fmac_f32_e32 v30, v37, v133
	v_fmac_f32_e32 v31, v41, v133
	v_fmac_f32_e32 v32, v45, v133
	v_fmac_f32_e32 v33, v49, v133
	v_fmac_f32_e32 v34, v53, v133
	v_fmac_f32_e32 v30, v38, v134
	v_fmac_f32_e32 v31, v42, v134
	v_fmac_f32_e32 v32, v46, v134
	v_fmac_f32_e32 v33, v50, v134
	v_fmac_f32_e32 v34, v54, v134
	v_fmac_f32_e32 v30, v39, v135
	v_fmac_f32_e32 v31, v43, v135
	v_fmac_f32_e32 v32, v47, v135
	v_fmac_f32_e32 v33, v51, v135
	v_fmac_f32_e32 v34, v55, v135
	ds_read_b128 v[36:39], v5 offset:160
	ds_read_b128 v[40:43], v5 offset:4256
	ds_read_b128 v[44:47], v5 offset:8352
	ds_read_b128 v[48:51], v5 offset:12448
	ds_read_b128 v[52:55], v5 offset:16544
	s_waitcnt lgkmcnt(4)
	v_fmac_f32_e32 v30, v36, v136
	s_waitcnt lgkmcnt(3)
	v_fmac_f32_e32 v31, v40, v136
	s_waitcnt lgkmcnt(2)
	v_fmac_f32_e32 v32, v44, v136
	s_waitcnt lgkmcnt(1)
	v_fmac_f32_e32 v33, v48, v136
	s_waitcnt lgkmcnt(0)
	v_fmac_f32_e32 v34, v52, v136
	v_fmac_f32_e32 v30, v37, v137
	v_fmac_f32_e32 v31, v41, v137
	v_fmac_f32_e32 v32, v45, v137
	v_fmac_f32_e32 v33, v49, v137
	v_fmac_f32_e32 v34, v53, v137
	v_fmac_f32_e32 v30, v38, v138
	v_fmac_f32_e32 v31, v42, v138
	v_fmac_f32_e32 v32, v46, v138
	v_fmac_f32_e32 v33, v50, v138
	v_fmac_f32_e32 v34, v54, v138
	v_fmac_f32_e32 v30, v39, v139
	v_fmac_f32_e32 v31, v43, v139
	v_fmac_f32_e32 v32, v47, v139
	v_fmac_f32_e32 v33, v51, v139
	v_fmac_f32_e32 v34, v55, v139
	ds_read_b128 v[36:39], v5 offset:176
	ds_read_b128 v[40:43], v5 offset:4272
	ds_read_b128 v[44:47], v5 offset:8368
	ds_read_b128 v[48:51], v5 offset:12464
	ds_read_b128 v[52:55], v5 offset:16560
	s_waitcnt lgkmcnt(4)
	v_fmac_f32_e32 v30, v36, v140
	s_waitcnt lgkmcnt(3)
	v_fmac_f32_e32 v31, v40, v140
	s_waitcnt lgkmcnt(2)
	v_fmac_f32_e32 v32, v44, v140
	s_waitcnt lgkmcnt(1)
	v_fmac_f32_e32 v33, v48, v140
	s_waitcnt lgkmcnt(0)
; __device__ __forceinline__ void mod_gemv_item(const Params& P, int item, float* sm) {
;     ...
;   const int kq = tid >> 6, jj = tid & 63;
;   float a0 = 0, a1 = 0, a2 = 0, a3 = 0, a4 = 0;
;   const float* w = P.w_mod + ((long)l * 1024 + kq * 256) * 6144 + jg * 64 + jj;
;   const float* s = sm + kq * 256;
; #pragma unroll 8
;   for (int k = 0; k < 256; ++k) {
;     const float wv = w[(long)k * 6144];
;     a0 += s[k] * wv; a1 += s[1024 + k] * wv; a2 += s[2048 + k] * wv; a3 += s[3072 + k] * wv; a4 += s[4096 + k] * wv;
;   }
	v_fmac_f32_e32 v34, v52, v140
	v_fmac_f32_e32 v30, v37, v141
	v_fmac_f32_e32 v31, v41, v141
	v_fmac_f32_e32 v32, v45, v141
	v_fmac_f32_e32 v33, v49, v141
	v_fmac_f32_e32 v34, v53, v141
	v_fmac_f32_e32 v30, v38, v142
	v_fmac_f32_e32 v31, v42, v142
	v_fmac_f32_e32 v32, v46, v142
	v_fmac_f32_e32 v33, v50, v142
	v_fmac_f32_e32 v34, v54, v142
	v_fmac_f32_e32 v30, v39, v143
	v_fmac_f32_e32 v31, v43, v143
	v_fmac_f32_e32 v32, v47, v143
	v_fmac_f32_e32 v33, v51, v143
	v_fmac_f32_e32 v34, v55, v143
	global_load_dword v112, v2, s[22:23]
	s_add_u32 s22, s22, 0x6000
	s_addc_u32 s23, s23, 0
	global_load_dword v113, v2, s[22:23]
	s_add_u32 s22, s22, 0x6000
	s_addc_u32 s23, s23, 0
	global_load_dword v114, v2, s[22:23]
	s_add_u32 s22, s22, 0x6000
	s_addc_u32 s23, s23, 0
	global_load_dword v115, v2, s[22:23]
	s_add_u32 s22, s22, 0x6000
	s_addc_u32 s23, s23, 0
	global_load_dword v116, v2, s[22:23]
	s_add_u32 s22, s22, 0x6000
	s_addc_u32 s23, s23, 0
	global_load_dword v117, v2, s[22:23]
	s_add_u32 s22, s22, 0x6000
	s_addc_u32 s23, s23, 0
	global_load_dword v118, v2, s[22:23]
	s_add_u32 s22, s22, 0x6000
	s_addc_u32 s23, s23, 0
	global_load_dword v119, v2, s[22:23]
	s_add_u32 s22, s22, 0x6000
	s_addc_u32 s23, s23, 0
	global_load_dword v120, v2, s[22:23]
	s_add_u32 s22, s22, 0x6000
	s_addc_u32 s23, s23, 0
	global_load_dword v121, v2, s[22:23]
	s_add_u32 s22, s22, 0x6000
	s_addc_u32 s23, s23, 0
	global_load_dword v122, v2, s[22:23]
	s_add_u32 s22, s22, 0x6000
	s_addc_u32 s23, s23, 0
	global_load_dword v123, v2, s[22:23]
	s_add_u32 s22, s22, 0x6000
	s_addc_u32 s23, s23, 0
	global_load_dword v124, v2, s[22:23]
	s_add_u32 s22, s22, 0x6000
	s_addc_u32 s23, s23, 0
	global_load_dword v125, v2, s[22:23]
	s_add_u32 s22, s22, 0x6000
	s_addc_u32 s23, s23, 0
	global_load_dword v126, v2, s[22:23]
	s_add_u32 s22, s22, 0x6000
	s_addc_u32 s23, s23, 0
	global_load_dword v127, v2, s[22:23]
	s_add_u32 s22, s22, 0x6000
	s_addc_u32 s23, s23, 0
	s_waitcnt vmcnt(32)
	ds_read_b128 v[36:39], v5 offset:192
	ds_read_b128 v[40:43], v5 offset:4288
	ds_read_b128 v[44:47], v5 offset:8384
	ds_read_b128 v[48:51], v5 offset:12480
	ds_read_b128 v[52:55], v5 offset:16576
	s_waitcnt lgkmcnt(4)
	v_fmac_f32_e32 v30, v36, v160
	s_waitcnt lgkmcnt(3)
	v_fmac_f32_e32 v31, v40, v160
	s_waitcnt lgkmcnt(2)
	v_fmac_f32_e32 v32, v44, v160
	s_waitcnt lgkmcnt(1)
	v_fmac_f32_e32 v33, v48, v160
	s_waitcnt lgkmcnt(0)
	v_fmac_f32_e32 v34, v52, v160
	v_fmac_f32_e32 v30, v37, v161
	v_fmac_f32_e32 v31, v41, v161
	v_fmac_f32_e32 v32, v45, v161
	v_fmac_f32_e32 v33, v49, v161
	v_fmac_f32_e32 v34, v53, v161
	v_fmac_f32_e32 v30, v38, v162
	v_fmac_f32_e32 v31, v42, v162
	v_fmac_f32_e32 v32, v46, v162
	v_fmac_f32_e32 v33, v50, v162
	v_fmac_f32_e32 v34, v54, v162
	v_fmac_f32_e32 v30, v39, v163
	v_fmac_f32_e32 v31, v43, v163
	v_fmac_f32_e32 v32, v47, v163
	v_fmac_f32_e32 v33, v51, v163
	v_fmac_f32_e32 v34, v55, v163
	ds_read_b128 v[36:39], v5 offset:208
	ds_read_b128 v[40:43], v5 offset:4304
	ds_read_b128 v[44:47], v5 offset:8400
	ds_read_b128 v[48:51], v5 offset:12496
	ds_read_b128 v[52:55], v5 offset:16592
	s_waitcnt lgkmcnt(4)
	v_fmac_f32_e32 v30, v36, v164
	s_waitcnt lgkmcnt(3)
	v_fmac_f32_e32 v31, v40, v164
	s_waitcnt lgkmcnt(2)
	v_fmac_f32_e32 v32, v44, v164
	s_waitcnt lgkmcnt(1)
	v_fmac_f32_e32 v33, v48, v164
	s_waitcnt lgkmcnt(0)
	v_fmac_f32_e32 v34, v52, v164
	v_fmac_f32_e32 v30, v37, v165
	v_fmac_f32_e32 v31, v41, v165
	v_fmac_f32_e32 v32, v45, v165
	v_fmac_f32_e32 v33, v49, v165
	v_fmac_f32_e32 v34, v53, v165
	v_fmac_f32_e32 v30, v38, v166
	v_fmac_f32_e32 v31, v42, v166
	v_fmac_f32_e32 v32, v46, v166
	v_fmac_f32_e32 v33, v50, v166
	v_fmac_f32_e32 v34, v54, v166
	v_fmac_f32_e32 v30, v39, v167
	v_fmac_f32_e32 v31, v43, v167
	v_fmac_f32_e32 v32, v47, v167
	v_fmac_f32_e32 v33, v51, v167
	v_fmac_f32_e32 v34, v55, v167
	ds_read_b128 v[36:39], v5 offset:224
	ds_read_b128 v[40:43], v5 offset:4320
	ds_read_b128 v[44:47], v5 offset:8416
	ds_read_b128 v[48:51], v5 offset:12512
	ds_read_b128 v[52:55], v5 offset:16608
	s_waitcnt lgkmcnt(4)
	v_fmac_f32_e32 v30, v36, v168
	s_waitcnt lgkmcnt(3)
	v_fmac_f32_e32 v31, v40, v168
	s_waitcnt lgkmcnt(2)
	v_fmac_f32_e32 v32, v44, v168
	s_waitcnt lgkmcnt(1)
	v_fmac_f32_e32 v33, v48, v168
	s_waitcnt lgkmcnt(0)
	v_fmac_f32_e32 v34, v52, v168
	v_fmac_f32_e32 v30, v37, v169
	v_fmac_f32_e32 v31, v41, v169
	v_fmac_f32_e32 v32, v45, v169
	v_fmac_f32_e32 v33, v49, v169
	v_fmac_f32_e32 v34, v53, v169
	v_fmac_f32_e32 v30, v38, v170
	v_fmac_f32_e32 v31, v42, v170
	v_fmac_f32_e32 v32, v46, v170
	v_fmac_f32_e32 v33, v50, v170
	v_fmac_f32_e32 v34, v54, v170
	v_fmac_f32_e32 v30, v39, v171
	v_fmac_f32_e32 v31, v43, v171
	v_fmac_f32_e32 v32, v47, v171
	v_fmac_f32_e32 v33, v51, v171
	v_fmac_f32_e32 v34, v55, v171
	ds_read_b128 v[36:39], v5 offset:240
	ds_read_b128 v[40:43], v5 offset:4336
	ds_read_b128 v[44:47], v5 offset:8432
	ds_read_b128 v[48:51], v5 offset:12528
	ds_read_b128 v[52:55], v5 offset:16624
	s_waitcnt lgkmcnt(4)
	v_fmac_f32_e32 v30, v36, v172
	s_waitcnt lgkmcnt(3)
	v_fmac_f32_e32 v31, v40, v172
	s_waitcnt lgkmcnt(2)
	v_fmac_f32_e32 v32, v44, v172
	s_waitcnt lgkmcnt(1)
	v_fmac_f32_e32 v33, v48, v172
	s_waitcnt lgkmcnt(0)
; __device__ __forceinline__ void mod_gemv_item(const Params& P, int item, float* sm) {
;     ...
;   const int kq = tid >> 6, jj = tid & 63;
;   float a0 = 0, a1 = 0, a2 = 0, a3 = 0, a4 = 0;
;   const float* w = P.w_mod + ((long)l * 1024 + kq * 256) * 6144 + jg * 64 + jj;
;   const float* s = sm + kq * 256;
; #pragma unroll 8
;   for (int k = 0; k < 256; ++k) {
;     const float wv = w[(long)k * 6144];
;     a0 += s[k] * wv; a1 += s[1024 + k] * wv; a2 += s[2048 + k] * wv; a3 += s[3072 + k] * wv; a4 += s[4096 + k] * wv;
;   }
	v_fmac_f32_e32 v34, v52, v172
	v_fmac_f32_e32 v30, v37, v173
	v_fmac_f32_e32 v31, v41, v173
	v_fmac_f32_e32 v32, v45, v173
	v_fmac_f32_e32 v33, v49, v173
	v_fmac_f32_e32 v34, v53, v173
	v_fmac_f32_e32 v30, v38, v174
	v_fmac_f32_e32 v31, v42, v174
	v_fmac_f32_e32 v32, v46, v174
	v_fmac_f32_e32 v33, v50, v174
	v_fmac_f32_e32 v34, v54, v174
	v_fmac_f32_e32 v30, v39, v175
	v_fmac_f32_e32 v31, v43, v175
	v_fmac_f32_e32 v32, v47, v175
	v_fmac_f32_e32 v33, v51, v175
	v_fmac_f32_e32 v34, v55, v175
	global_load_dword v128, v2, s[22:23]
	s_add_u32 s22, s22, 0x6000
	s_addc_u32 s23, s23, 0
	global_load_dword v129, v2, s[22:23]
	s_add_u32 s22, s22, 0x6000
	s_addc_u32 s23, s23, 0
	global_load_dword v130, v2, s[22:23]
	s_add_u32 s22, s22, 0x6000
	s_addc_u32 s23, s23, 0
	global_load_dword v131, v2, s[22:23]
	s_add_u32 s22, s22, 0x6000
	s_addc_u32 s23, s23, 0
	global_load_dword v132, v2, s[22:23]
	s_add_u32 s22, s22, 0x6000
	s_addc_u32 s23, s23, 0
	global_load_dword v133, v2, s[22:23]
	s_add_u32 s22, s22, 0x6000
	s_addc_u32 s23, s23, 0
	global_load_dword v134, v2, s[22:23]
	s_add_u32 s22, s22, 0x6000
	s_addc_u32 s23, s23, 0
	global_load_dword v135, v2, s[22:23]
	s_add_u32 s22, s22, 0x6000
	s_addc_u32 s23, s23, 0
	global_load_dword v136, v2, s[22:23]
	s_add_u32 s22, s22, 0x6000
	s_addc_u32 s23, s23, 0
	global_load_dword v137, v2, s[22:23]
	s_add_u32 s22, s22, 0x6000
	s_addc_u32 s23, s23, 0
	global_load_dword v138, v2, s[22:23]
	s_add_u32 s22, s22, 0x6000
	s_addc_u32 s23, s23, 0
	global_load_dword v139, v2, s[22:23]
	s_add_u32 s22, s22, 0x6000
	s_addc_u32 s23, s23, 0
	global_load_dword v140, v2, s[22:23]
	s_add_u32 s22, s22, 0x6000
	s_addc_u32 s23, s23, 0
	global_load_dword v141, v2, s[22:23]
	s_add_u32 s22, s22, 0x6000
	s_addc_u32 s23, s23, 0
	global_load_dword v142, v2, s[22:23]
	s_add_u32 s22, s22, 0x6000
	s_addc_u32 s23, s23, 0
	global_load_dword v143, v2, s[22:23]
	s_add_u32 s22, s22, 0x6000
	s_addc_u32 s23, s23, 0
	s_waitcnt vmcnt(32)
	ds_read_b128 v[36:39], v5 offset:256
	ds_read_b128 v[40:43], v5 offset:4352
	ds_read_b128 v[44:47], v5 offset:8448
	ds_read_b128 v[48:51], v5 offset:12544
	ds_read_b128 v[52:55], v5 offset:16640
	s_waitcnt lgkmcnt(4)
	v_fmac_f32_e32 v30, v36, v96
	s_waitcnt lgkmcnt(3)
	v_fmac_f32_e32 v31, v40, v96
	s_waitcnt lgkmcnt(2)
	v_fmac_f32_e32 v32, v44, v96
	s_waitcnt lgkmcnt(1)
	v_fmac_f32_e32 v33, v48, v96
	s_waitcnt lgkmcnt(0)
	v_fmac_f32_e32 v34, v52, v96
	v_fmac_f32_e32 v30, v37, v97
	v_fmac_f32_e32 v31, v41, v97
	v_fmac_f32_e32 v32, v45, v97
	v_fmac_f32_e32 v33, v49, v97
	v_fmac_f32_e32 v34, v53, v97
	v_fmac_f32_e32 v30, v38, v98
	v_fmac_f32_e32 v31, v42, v98
	v_fmac_f32_e32 v32, v46, v98
	v_fmac_f32_e32 v33, v50, v98
	v_fmac_f32_e32 v34, v54, v98
	v_fmac_f32_e32 v30, v39, v99
	v_fmac_f32_e32 v31, v43, v99
	v_fmac_f32_e32 v32, v47, v99
	v_fmac_f32_e32 v33, v51, v99
	v_fmac_f32_e32 v34, v55, v99
	ds_read_b128 v[36:39], v5 offset:272
	ds_read_b128 v[40:43], v5 offset:4368
	ds_read_b128 v[44:47], v5 offset:8464
	ds_read_b128 v[48:51], v5 offset:12560
	ds_read_b128 v[52:55], v5 offset:16656
	s_waitcnt lgkmcnt(4)
	v_fmac_f32_e32 v30, v36, v100
	s_waitcnt lgkmcnt(3)
	v_fmac_f32_e32 v31, v40, v100
	s_waitcnt lgkmcnt(2)
	v_fmac_f32_e32 v32, v44, v100
	s_waitcnt lgkmcnt(1)
	v_fmac_f32_e32 v33, v48, v100
	s_waitcnt lgkmcnt(0)
	v_fmac_f32_e32 v34, v52, v100
	v_fmac_f32_e32 v30, v37, v101
	v_fmac_f32_e32 v31, v41, v101
	v_fmac_f32_e32 v32, v45, v101
	v_fmac_f32_e32 v33, v49, v101
	v_fmac_f32_e32 v34, v53, v101
	v_fmac_f32_e32 v30, v38, v102
	v_fmac_f32_e32 v31, v42, v102
	v_fmac_f32_e32 v32, v46, v102
	v_fmac_f32_e32 v33, v50, v102
	v_fmac_f32_e32 v34, v54, v102
	v_fmac_f32_e32 v30, v39, v103
	v_fmac_f32_e32 v31, v43, v103
	v_fmac_f32_e32 v32, v47, v103
	v_fmac_f32_e32 v33, v51, v103
	v_fmac_f32_e32 v34, v55, v103
	ds_read_b128 v[36:39], v5 offset:288
	ds_read_b128 v[40:43], v5 offset:4384
	ds_read_b128 v[44:47], v5 offset:8480
	ds_read_b128 v[48:51], v5 offset:12576
	ds_read_b128 v[52:55], v5 offset:16672
	s_waitcnt lgkmcnt(4)
	v_fmac_f32_e32 v30, v36, v104
	s_waitcnt lgkmcnt(3)
	v_fmac_f32_e32 v31, v40, v104
	s_waitcnt lgkmcnt(2)
	v_fmac_f32_e32 v32, v44, v104
	s_waitcnt lgkmcnt(1)
	v_fmac_f32_e32 v33, v48, v104
	s_waitcnt lgkmcnt(0)
	v_fmac_f32_e32 v34, v52, v104
	v_fmac_f32_e32 v30, v37, v105
	v_fmac_f32_e32 v31, v41, v105
	v_fmac_f32_e32 v32, v45, v105
	v_fmac_f32_e32 v33, v49, v105
	v_fmac_f32_e32 v34, v53, v105
	v_fmac_f32_e32 v30, v38, v106
	v_fmac_f32_e32 v31, v42, v106
	v_fmac_f32_e32 v32, v46, v106
	v_fmac_f32_e32 v33, v50, v106
	v_fmac_f32_e32 v34, v54, v106
	v_fmac_f32_e32 v30, v39, v107
	v_fmac_f32_e32 v31, v43, v107
	v_fmac_f32_e32 v32, v47, v107
	v_fmac_f32_e32 v33, v51, v107
	v_fmac_f32_e32 v34, v55, v107
	ds_read_b128 v[36:39], v5 offset:304
	ds_read_b128 v[40:43], v5 offset:4400
	ds_read_b128 v[44:47], v5 offset:8496
	ds_read_b128 v[48:51], v5 offset:12592
	ds_read_b128 v[52:55], v5 offset:16688
	s_waitcnt lgkmcnt(4)
	v_fmac_f32_e32 v30, v36, v108
	s_waitcnt lgkmcnt(3)
	v_fmac_f32_e32 v31, v40, v108
	s_waitcnt lgkmcnt(2)
	v_fmac_f32_e32 v32, v44, v108
	s_waitcnt lgkmcnt(1)
	v_fmac_f32_e32 v33, v48, v108
	s_waitcnt lgkmcnt(0)
; __device__ __forceinline__ void mod_gemv_item(const Params& P, int item, float* sm) {
;     ...
;   const int kq = tid >> 6, jj = tid & 63;
;   float a0 = 0, a1 = 0, a2 = 0, a3 = 0, a4 = 0;
;   const float* w = P.w_mod + ((long)l * 1024 + kq * 256) * 6144 + jg * 64 + jj;
;   const float* s = sm + kq * 256;
; #pragma unroll 8
;   for (int k = 0; k < 256; ++k) {
;     const float wv = w[(long)k * 6144];
;     a0 += s[k] * wv; a1 += s[1024 + k] * wv; a2 += s[2048 + k] * wv; a3 += s[3072 + k] * wv; a4 += s[4096 + k] * wv;
;   }
	v_fmac_f32_e32 v34, v52, v108
	v_fmac_f32_e32 v30, v37, v109
	v_fmac_f32_e32 v31, v41, v109
	v_fmac_f32_e32 v32, v45, v109
	v_fmac_f32_e32 v33, v49, v109
	v_fmac_f32_e32 v34, v53, v109
	v_fmac_f32_e32 v30, v38, v110
	v_fmac_f32_e32 v31, v42, v110
	v_fmac_f32_e32 v32, v46, v110
	v_fmac_f32_e32 v33, v50, v110
	v_fmac_f32_e32 v34, v54, v110
	v_fmac_f32_e32 v30, v39, v111
	v_fmac_f32_e32 v31, v43, v111
	v_fmac_f32_e32 v32, v47, v111
	v_fmac_f32_e32 v33, v51, v111
	v_fmac_f32_e32 v34, v55, v111
	global_load_dword v160, v2, s[22:23]
	s_add_u32 s22, s22, 0x6000
	s_addc_u32 s23, s23, 0
	global_load_dword v161, v2, s[22:23]
	s_add_u32 s22, s22, 0x6000
	s_addc_u32 s23, s23, 0
	global_load_dword v162, v2, s[22:23]
	s_add_u32 s22, s22, 0x6000
	s_addc_u32 s23, s23, 0
	global_load_dword v163, v2, s[22:23]
	s_add_u32 s22, s22, 0x6000
	s_addc_u32 s23, s23, 0
	global_load_dword v164, v2, s[22:23]
	s_add_u32 s22, s22, 0x6000
	s_addc_u32 s23, s23, 0
	global_load_dword v165, v2, s[22:23]
	s_add_u32 s22, s22, 0x6000
	s_addc_u32 s23, s23, 0
	global_load_dword v166, v2, s[22:23]
	s_add_u32 s22, s22, 0x6000
	s_addc_u32 s23, s23, 0
	global_load_dword v167, v2, s[22:23]
	s_add_u32 s22, s22, 0x6000
	s_addc_u32 s23, s23, 0
	global_load_dword v168, v2, s[22:23]
	s_add_u32 s22, s22, 0x6000
	s_addc_u32 s23, s23, 0
	global_load_dword v169, v2, s[22:23]
	s_add_u32 s22, s22, 0x6000
	s_addc_u32 s23, s23, 0
	global_load_dword v170, v2, s[22:23]
	s_add_u32 s22, s22, 0x6000
	s_addc_u32 s23, s23, 0
	global_load_dword v171, v2, s[22:23]
	s_add_u32 s22, s22, 0x6000
	s_addc_u32 s23, s23, 0
	global_load_dword v172, v2, s[22:23]
	s_add_u32 s22, s22, 0x6000
	s_addc_u32 s23, s23, 0
	global_load_dword v173, v2, s[22:23]
	s_add_u32 s22, s22, 0x6000
	s_addc_u32 s23, s23, 0
	global_load_dword v174, v2, s[22:23]
	s_add_u32 s22, s22, 0x6000
	s_addc_u32 s23, s23, 0
	global_load_dword v175, v2, s[22:23]
	s_add_u32 s22, s22, 0x6000
	s_addc_u32 s23, s23, 0
	s_waitcnt vmcnt(32)
	ds_read_b128 v[36:39], v5 offset:320
	ds_read_b128 v[40:43], v5 offset:4416
	ds_read_b128 v[44:47], v5 offset:8512
	ds_read_b128 v[48:51], v5 offset:12608
	ds_read_b128 v[52:55], v5 offset:16704
	s_waitcnt lgkmcnt(4)
	v_fmac_f32_e32 v30, v36, v112
	s_waitcnt lgkmcnt(3)
	v_fmac_f32_e32 v31, v40, v112
	s_waitcnt lgkmcnt(2)
	v_fmac_f32_e32 v32, v44, v112
	s_waitcnt lgkmcnt(1)
	v_fmac_f32_e32 v33, v48, v112
	s_waitcnt lgkmcnt(0)
	v_fmac_f32_e32 v34, v52, v112
	v_fmac_f32_e32 v30, v37, v113
	v_fmac_f32_e32 v31, v41, v113
	v_fmac_f32_e32 v32, v45, v113
	v_fmac_f32_e32 v33, v49, v113
	v_fmac_f32_e32 v34, v53, v113
	v_fmac_f32_e32 v30, v38, v114
	v_fmac_f32_e32 v31, v42, v114
	v_fmac_f32_e32 v32, v46, v114
	v_fmac_f32_e32 v33, v50, v114
	v_fmac_f32_e32 v34, v54, v114
	v_fmac_f32_e32 v30, v39, v115
	v_fmac_f32_e32 v31, v43, v115
	v_fmac_f32_e32 v32, v47, v115
	v_fmac_f32_e32 v33, v51, v115
	v_fmac_f32_e32 v34, v55, v115
	ds_read_b128 v[36:39], v5 offset:336
	ds_read_b128 v[40:43], v5 offset:4432
	ds_read_b128 v[44:47], v5 offset:8528
	ds_read_b128 v[48:51], v5 offset:12624
	ds_read_b128 v[52:55], v5 offset:16720
	s_waitcnt lgkmcnt(4)
	v_fmac_f32_e32 v30, v36, v116
	s_waitcnt lgkmcnt(3)
	v_fmac_f32_e32 v31, v40, v116
	s_waitcnt lgkmcnt(2)
	v_fmac_f32_e32 v32, v44, v116
	s_waitcnt lgkmcnt(1)
	v_fmac_f32_e32 v33, v48, v116
	s_waitcnt lgkmcnt(0)
	v_fmac_f32_e32 v34, v52, v116
	v_fmac_f32_e32 v30, v37, v117
	v_fmac_f32_e32 v31, v41, v117
	v_fmac_f32_e32 v32, v45, v117
	v_fmac_f32_e32 v33, v49, v117
	v_fmac_f32_e32 v34, v53, v117
	v_fmac_f32_e32 v30, v38, v118
	v_fmac_f32_e32 v31, v42, v118
	v_fmac_f32_e32 v32, v46, v118
	v_fmac_f32_e32 v33, v50, v118
	v_fmac_f32_e32 v34, v54, v118
	v_fmac_f32_e32 v30, v39, v119
	v_fmac_f32_e32 v31, v43, v119
	v_fmac_f32_e32 v32, v47, v119
	v_fmac_f32_e32 v33, v51, v119
	v_fmac_f32_e32 v34, v55, v119
	ds_read_b128 v[36:39], v5 offset:352
	ds_read_b128 v[40:43], v5 offset:4448
	ds_read_b128 v[44:47], v5 offset:8544
	ds_read_b128 v[48:51], v5 offset:12640
	ds_read_b128 v[52:55], v5 offset:16736
	s_waitcnt lgkmcnt(4)
	v_fmac_f32_e32 v30, v36, v120
	s_waitcnt lgkmcnt(3)
	v_fmac_f32_e32 v31, v40, v120
	s_waitcnt lgkmcnt(2)
	v_fmac_f32_e32 v32, v44, v120
	s_waitcnt lgkmcnt(1)
	v_fmac_f32_e32 v33, v48, v120
	s_waitcnt lgkmcnt(0)
	v_fmac_f32_e32 v34, v52, v120
	v_fmac_f32_e32 v30, v37, v121
	v_fmac_f32_e32 v31, v41, v121
	v_fmac_f32_e32 v32, v45, v121
	v_fmac_f32_e32 v33, v49, v121
	v_fmac_f32_e32 v34, v53, v121
	v_fmac_f32_e32 v30, v38, v122
	v_fmac_f32_e32 v31, v42, v122
	v_fmac_f32_e32 v32, v46, v122
	v_fmac_f32_e32 v33, v50, v122
	v_fmac_f32_e32 v34, v54, v122
	v_fmac_f32_e32 v30, v39, v123
	v_fmac_f32_e32 v31, v43, v123
	v_fmac_f32_e32 v32, v47, v123
	v_fmac_f32_e32 v33, v51, v123
	v_fmac_f32_e32 v34, v55, v123
	ds_read_b128 v[36:39], v5 offset:368
	ds_read_b128 v[40:43], v5 offset:4464
	ds_read_b128 v[44:47], v5 offset:8560
	ds_read_b128 v[48:51], v5 offset:12656
	ds_read_b128 v[52:55], v5 offset:16752
	s_waitcnt lgkmcnt(4)
	v_fmac_f32_e32 v30, v36, v124
	s_waitcnt lgkmcnt(3)
	v_fmac_f32_e32 v31, v40, v124
	s_waitcnt lgkmcnt(2)
	v_fmac_f32_e32 v32, v44, v124
	s_waitcnt lgkmcnt(1)
	v_fmac_f32_e32 v33, v48, v124
	s_waitcnt lgkmcnt(0)
	v_fmac_f32_e32 v34, v52, v124
	v_fmac_f32_e32 v30, v37, v125
	v_fmac_f32_e32 v31, v41, v125
	v_fmac_f32_e32 v32, v45, v125
	v_fmac_f32_e32 v33, v49, v125
	v_fmac_f32_e32 v34, v53, v125
	v_fmac_f32_e32 v30, v38, v126
	v_fmac_f32_e32 v31, v42, v126
	v_fmac_f32_e32 v32, v46, v126
	v_fmac_f32_e32 v33, v50, v126
	v_fmac_f32_e32 v34, v54, v126
	v_fmac_f32_e32 v30, v39, v127
	v_fmac_f32_e32 v31, v43, v127
	v_fmac_f32_e32 v32, v47, v127
	v_fmac_f32_e32 v33, v51, v127
	v_fmac_f32_e32 v34, v55, v127
	s_waitcnt vmcnt(16)
; __device__ __forceinline__ void mod_gemv_item(const Params& P, int item, float* sm) {
;     ...
;   const int kq = tid >> 6, jj = tid & 63;
;   float a0 = 0, a1 = 0, a2 = 0, a3 = 0, a4 = 0;
;   const float* w = P.w_mod + ((long)l * 1024 + kq * 256) * 6144 + jg * 64 + jj;
;   const float* s = sm + kq * 256;
; #pragma unroll 8
;   for (int k = 0; k < 256; ++k) {
;     const float wv = w[(long)k * 6144];
;     a0 += s[k] * wv; a1 += s[1024 + k] * wv; a2 += s[2048 + k] * wv; a3 += s[3072 + k] * wv; a4 += s[4096 + k] * wv;
;   }
	ds_read_b128 v[36:39], v5 offset:384
	ds_read_b128 v[40:43], v5 offset:4480
	ds_read_b128 v[44:47], v5 offset:8576
	ds_read_b128 v[48:51], v5 offset:12672
	ds_read_b128 v[52:55], v5 offset:16768
	s_waitcnt lgkmcnt(4)
	v_fmac_f32_e32 v30, v36, v128
	s_waitcnt lgkmcnt(3)
	v_fmac_f32_e32 v31, v40, v128
	s_waitcnt lgkmcnt(2)
	v_fmac_f32_e32 v32, v44, v128
	s_waitcnt lgkmcnt(1)
	v_fmac_f32_e32 v33, v48, v128
	s_waitcnt lgkmcnt(0)
	v_fmac_f32_e32 v34, v52, v128
	v_fmac_f32_e32 v30, v37, v129
	v_fmac_f32_e32 v31, v41, v129
	v_fmac_f32_e32 v32, v45, v129
	v_fmac_f32_e32 v33, v49, v129
	v_fmac_f32_e32 v34, v53, v129
	v_fmac_f32_e32 v30, v38, v130
	v_fmac_f32_e32 v31, v42, v130
	v_fmac_f32_e32 v32, v46, v130
	v_fmac_f32_e32 v33, v50, v130
	v_fmac_f32_e32 v34, v54, v130
	v_fmac_f32_e32 v30, v39, v131
	v_fmac_f32_e32 v31, v43, v131
	v_fmac_f32_e32 v32, v47, v131
	v_fmac_f32_e32 v33, v51, v131
	v_fmac_f32_e32 v34, v55, v131
	ds_read_b128 v[36:39], v5 offset:400
	ds_read_b128 v[40:43], v5 offset:4496
	ds_read_b128 v[44:47], v5 offset:8592
	ds_read_b128 v[48:51], v5 offset:12688
	ds_read_b128 v[52:55], v5 offset:16784
	s_waitcnt lgkmcnt(4)
	v_fmac_f32_e32 v30, v36, v132
	s_waitcnt lgkmcnt(3)
	v_fmac_f32_e32 v31, v40, v132
	s_waitcnt lgkmcnt(2)
	v_fmac_f32_e32 v32, v44, v132
	s_waitcnt lgkmcnt(1)
	v_fmac_f32_e32 v33, v48, v132
	s_waitcnt lgkmcnt(0)
	v_fmac_f32_e32 v34, v52, v132
	v_fmac_f32_e32 v30, v37, v133
	v_fmac_f32_e32 v31, v41, v133
	v_fmac_f32_e32 v32, v45, v133
	v_fmac_f32_e32 v33, v49, v133
	v_fmac_f32_e32 v34, v53, v133
	v_fmac_f32_e32 v30, v38, v134
	v_fmac_f32_e32 v31, v42, v134
	v_fmac_f32_e32 v32, v46, v134
	v_fmac_f32_e32 v33, v50, v134
	v_fmac_f32_e32 v34, v54, v134
	v_fmac_f32_e32 v30, v39, v135
	v_fmac_f32_e32 v31, v43, v135
	v_fmac_f32_e32 v32, v47, v135
	v_fmac_f32_e32 v33, v51, v135
	v_fmac_f32_e32 v34, v55, v135
	ds_read_b128 v[36:39], v5 offset:416
	ds_read_b128 v[40:43], v5 offset:4512
	ds_read_b128 v[44:47], v5 offset:8608
	ds_read_b128 v[48:51], v5 offset:12704
	ds_read_b128 v[52:55], v5 offset:16800
	s_waitcnt lgkmcnt(4)
	v_fmac_f32_e32 v30, v36, v136
	s_waitcnt lgkmcnt(3)
	v_fmac_f32_e32 v31, v40, v136
	s_waitcnt lgkmcnt(2)
	v_fmac_f32_e32 v32, v44, v136
	s_waitcnt lgkmcnt(1)
	v_fmac_f32_e32 v33, v48, v136
	s_waitcnt lgkmcnt(0)
	v_fmac_f32_e32 v34, v52, v136
	v_fmac_f32_e32 v30, v37, v137
	v_fmac_f32_e32 v31, v41, v137
	v_fmac_f32_e32 v32, v45, v137
	v_fmac_f32_e32 v33, v49, v137
	v_fmac_f32_e32 v34, v53, v137
	v_fmac_f32_e32 v30, v38, v138
	v_fmac_f32_e32 v31, v42, v138
	v_fmac_f32_e32 v32, v46, v138
	v_fmac_f32_e32 v33, v50, v138
	v_fmac_f32_e32 v34, v54, v138
	v_fmac_f32_e32 v30, v39, v139
	v_fmac_f32_e32 v31, v43, v139
	v_fmac_f32_e32 v32, v47, v139
	v_fmac_f32_e32 v33, v51, v139
	v_fmac_f32_e32 v34, v55, v139
	ds_read_b128 v[36:39], v5 offset:432
	ds_read_b128 v[40:43], v5 offset:4528
	ds_read_b128 v[44:47], v5 offset:8624
	ds_read_b128 v[48:51], v5 offset:12720
	ds_read_b128 v[52:55], v5 offset:16816
	s_waitcnt lgkmcnt(4)
	v_fmac_f32_e32 v30, v36, v140
	s_waitcnt lgkmcnt(3)
	v_fmac_f32_e32 v31, v40, v140
	s_waitcnt lgkmcnt(2)
	v_fmac_f32_e32 v32, v44, v140
	s_waitcnt lgkmcnt(1)
	v_fmac_f32_e32 v33, v48, v140
	s_waitcnt lgkmcnt(0)
	v_fmac_f32_e32 v34, v52, v140
	v_fmac_f32_e32 v30, v37, v141
	v_fmac_f32_e32 v31, v41, v141
	v_fmac_f32_e32 v32, v45, v141
	v_fmac_f32_e32 v33, v49, v141
	v_fmac_f32_e32 v34, v53, v141
	v_fmac_f32_e32 v30, v38, v142
	v_fmac_f32_e32 v31, v42, v142
	v_fmac_f32_e32 v32, v46, v142
	v_fmac_f32_e32 v33, v50, v142
	v_fmac_f32_e32 v34, v54, v142
	v_fmac_f32_e32 v30, v39, v143
	v_fmac_f32_e32 v31, v43, v143
	v_fmac_f32_e32 v32, v47, v143
	v_fmac_f32_e32 v33, v51, v143
	v_fmac_f32_e32 v34, v55, v143
	s_waitcnt vmcnt(0)
	ds_read_b128 v[36:39], v5 offset:448
	ds_read_b128 v[40:43], v5 offset:4544
	ds_read_b128 v[44:47], v5 offset:8640
	ds_read_b128 v[48:51], v5 offset:12736
	ds_read_b128 v[52:55], v5 offset:16832
	s_waitcnt lgkmcnt(4)
	v_fmac_f32_e32 v30, v36, v160
	s_waitcnt lgkmcnt(3)
	v_fmac_f32_e32 v31, v40, v160
	s_waitcnt lgkmcnt(2)
	v_fmac_f32_e32 v32, v44, v160
	s_waitcnt lgkmcnt(1)
	v_fmac_f32_e32 v33, v48, v160
	s_waitcnt lgkmcnt(0)
	v_fmac_f32_e32 v34, v52, v160
	v_fmac_f32_e32 v30, v37, v161
	v_fmac_f32_e32 v31, v41, v161
	v_fmac_f32_e32 v32, v45, v161
	v_fmac_f32_e32 v33, v49, v161
	v_fmac_f32_e32 v34, v53, v161
	v_fmac_f32_e32 v30, v38, v162
	v_fmac_f32_e32 v31, v42, v162
	v_fmac_f32_e32 v32, v46, v162
	v_fmac_f32_e32 v33, v50, v162
	v_fmac_f32_e32 v34, v54, v162
	v_fmac_f32_e32 v30, v39, v163
	v_fmac_f32_e32 v31, v43, v163
	v_fmac_f32_e32 v32, v47, v163
	v_fmac_f32_e32 v33, v51, v163
	v_fmac_f32_e32 v34, v55, v163
	ds_read_b128 v[36:39], v5 offset:464
	ds_read_b128 v[40:43], v5 offset:4560
	ds_read_b128 v[44:47], v5 offset:8656
	ds_read_b128 v[48:51], v5 offset:12752
	ds_read_b128 v[52:55], v5 offset:16848
	s_waitcnt lgkmcnt(4)
	v_fmac_f32_e32 v30, v36, v164
	s_waitcnt lgkmcnt(3)
	v_fmac_f32_e32 v31, v40, v164
	s_waitcnt lgkmcnt(2)
	v_fmac_f32_e32 v32, v44, v164
	s_waitcnt lgkmcnt(1)
	v_fmac_f32_e32 v33, v48, v164
	s_waitcnt lgkmcnt(0)
	v_fmac_f32_e32 v34, v52, v164
	v_fmac_f32_e32 v30, v37, v165
	v_fmac_f32_e32 v31, v41, v165
	v_fmac_f32_e32 v32, v45, v165
	v_fmac_f32_e32 v33, v49, v165
	v_fmac_f32_e32 v34, v53, v165
	v_fmac_f32_e32 v30, v38, v166
	v_fmac_f32_e32 v31, v42, v166
	v_fmac_f32_e32 v32, v46, v166
	v_fmac_f32_e32 v33, v50, v166
	v_fmac_f32_e32 v34, v54, v166
	v_fmac_f32_e32 v30, v39, v167
	v_fmac_f32_e32 v31, v43, v167
	v_fmac_f32_e32 v32, v47, v167
	v_fmac_f32_e32 v33, v51, v167
	v_fmac_f32_e32 v34, v55, v167
	ds_read_b128 v[36:39], v5 offset:480
	ds_read_b128 v[40:43], v5 offset:4576
	ds_read_b128 v[44:47], v5 offset:8672
	ds_read_b128 v[48:51], v5 offset:12768
	ds_read_b128 v[52:55], v5 offset:16864
	s_waitcnt lgkmcnt(4)
; __device__ __forceinline__ void mod_gemv_item(const Params& P, int item, float* sm) {
;     ...
;   for (int k = 0; k < 256; ++k) {
;     const float wv = w[(long)k * 6144];
;     a0 += s[k] * wv; a1 += s[1024 + k] * wv; a2 += s[2048 + k] * wv; a3 += s[3072 + k] * wv; a4 += s[4096 + k] * wv;
;   }
;   float* red = sm + 5120;
;   red[(kq * 5 + 0) * 64 + jj] = a0; red[(kq * 5 + 1) * 64 + jj] = a1; red[(kq * 5 + 2) * 64 + jj] = a2;
;   red[(kq * 5 + 3) * 64 + jj] = a3; red[(kq * 5 + 4) * 64 + jj] = a4;
;   __syncthreads();
;   for (int idx = tid; idx < 320; idx += VTHR) {
;     const int m = idx >> 6, j = idx & 63;
;     const float v = red[(0 * 5 + m) * 64 + j] + red[(1 * 5 + m) * 64 + j] + red[(2 * 5 + m) * 64 + j] + red[(3 * 5 + m) * 64 + j];
;     const int col = jg * 64 + j;
;     P.mod[(long)(l * 5 + m) * 6144 + col] = v + P.b_mod[l * 6144 + col];
;   }
; __device__ __forceinline__ void prep_phase(const Params& P, float* sm) {
;     ...
;   for (int tt = VBID; tt < NTR; tt += VGRID) {
;     int t = tt;
;     const float* src; u16* dst; int ldn, ldk, mode = 0, kt, ntl;
;     if (t < 384) { src = P.w_in_ab; dst = P.wt_in; ldn = 1536; ldk = 1024; kt = t / 24; ntl = t % 24; }
;     else if (t < 640) { t -= 384; src = P.w_out_ab; dst = P.wt_outab; ldn = 1024; ldk = 1024; kt = t / 16; ntl = t % 16; }
;     else if (t < 1408) { t -= 640; src = P.w_qkv; dst = P.wt_qkv; ldn = 3072; ldk = 1024; kt = t / 48; ntl = t % 48; }
;     else if (t < 1664) { t -= 1408; src = P.w_out_na; dst = P.wt_outna; ldn = 1024; ldk = 1024; kt = t / 16; ntl = t % 16; }
;     else if (t < 1664 + 2816) {
;       t -= 1664;
;       const int which = t / 704, tq = t % 704;
;       const int l = which & 1, isup = which >> 1;
;       src = (isup ? P.w_up : P.w_gate) + (long)l * 1024 * 2816;
;       dst = P.wt_gu + (long)l * 5632 * 1024;
;       ldn = 2816; ldk = 1024; mode = isup ? 2 : 1; kt = tq / 44; ntl = tq % 44;
;     } else {
;       t -= 1664 + 2816;
;       const int l = t / 704, tq = t % 704;
;       src = P.w_down + (long)l * 2816 * 1024;
;       dst = P.wt_dn + (long)l * 1024 * 2816;
;       ldn = 1024; ldk = 2816; kt = tq / 16; ntl = tq % 16;
;     }
	v_fmac_f32_e32 v30, v36, v168
	s_waitcnt lgkmcnt(3)
	v_fmac_f32_e32 v31, v40, v168
	s_waitcnt lgkmcnt(2)
	v_fmac_f32_e32 v32, v44, v168
	s_waitcnt lgkmcnt(1)
	v_fmac_f32_e32 v33, v48, v168
	s_waitcnt lgkmcnt(0)
	v_fmac_f32_e32 v34, v52, v168
	v_fmac_f32_e32 v30, v37, v169
	v_fmac_f32_e32 v31, v41, v169
	v_fmac_f32_e32 v32, v45, v169
	v_fmac_f32_e32 v33, v49, v169
	v_fmac_f32_e32 v34, v53, v169
	v_fmac_f32_e32 v30, v38, v170
	v_fmac_f32_e32 v31, v42, v170
	v_fmac_f32_e32 v32, v46, v170
	v_fmac_f32_e32 v33, v50, v170
	v_fmac_f32_e32 v34, v54, v170
	v_fmac_f32_e32 v30, v39, v171
	v_fmac_f32_e32 v31, v43, v171
	v_fmac_f32_e32 v32, v47, v171
	v_fmac_f32_e32 v33, v51, v171
	v_fmac_f32_e32 v34, v55, v171
	ds_read_b128 v[36:39], v5 offset:496
	ds_read_b128 v[40:43], v5 offset:4592
	ds_read_b128 v[44:47], v5 offset:8688
	ds_read_b128 v[48:51], v5 offset:12784
	ds_read_b128 v[52:55], v5 offset:16880
	s_waitcnt lgkmcnt(4)
	v_fmac_f32_e32 v30, v36, v172
	s_waitcnt lgkmcnt(3)
	v_fmac_f32_e32 v31, v40, v172
	s_waitcnt lgkmcnt(2)
	v_fmac_f32_e32 v32, v44, v172
	s_waitcnt lgkmcnt(1)
	v_fmac_f32_e32 v33, v48, v172
	s_waitcnt lgkmcnt(0)
	v_fmac_f32_e32 v34, v52, v172
	v_fmac_f32_e32 v30, v37, v173
	v_fmac_f32_e32 v31, v41, v173
	v_fmac_f32_e32 v32, v45, v173
	v_fmac_f32_e32 v33, v49, v173
	v_fmac_f32_e32 v34, v53, v173
	v_fmac_f32_e32 v30, v38, v174
	v_fmac_f32_e32 v31, v42, v174
	v_fmac_f32_e32 v32, v46, v174
	v_fmac_f32_e32 v33, v50, v174
	v_fmac_f32_e32 v34, v54, v174
	v_fmac_f32_e32 v30, v39, v175
	v_fmac_f32_e32 v31, v43, v175
	v_fmac_f32_e32 v32, v47, v175
	v_fmac_f32_e32 v33, v51, v175
	v_fmac_f32_e32 v34, v55, v175
	s_mul_i32 s20, s3, 1280
	v_add_u32_e32 v6, s20, v2
	ds_write_b32 v6, v30 offset:20496
	ds_write_b32 v6, v31 offset:20752
	ds_write_b32 v6, v32 offset:21008
	ds_write_b32 v6, v33 offset:21264
	ds_write_b32 v6, v34 offset:21520
	s_waitcnt lgkmcnt(0)
	s_barrier
	s_cmp_lt_u32 s3, 5
	s_cbranch_scc0 .Lmy_p0_tr
	ds_read_b32 v36, v4 offset:20496
	ds_read_b32 v37, v4 offset:21776
	ds_read_b32 v38, v4 offset:23056
	ds_read_b32 v39, v4 offset:24336
	ds_read_b32 v40, v4 offset:25616
	ds_read_b32 v41, v4 offset:26896
	ds_read_b32 v42, v4 offset:28176
	ds_read_b32 v43, v4 offset:29456
	s_mul_i32 s20, s18, 0x6000
	s_lshl_b32 s21, s19, 8
	s_add_u32 s20, s20, s21
	s_add_u32 s24, s14, s20
	s_addc_u32 s25, s15, 0
	global_load_dword v44, v2, s[24:25]
	s_mul_i32 s20, s18, 5
	s_add_u32 s20, s20, s3
	s_mul_i32 s20, s20, 0x6000
	s_add_u32 s20, s20, s21
	s_add_u32 s24, s16, s20
	s_addc_u32 s25, s17, 0
	s_waitcnt lgkmcnt(0)
	v_add_f32_e32 v36, v36, v37
	v_add_f32_e32 v36, v36, v38
	v_add_f32_e32 v36, v36, v39
	v_add_f32_e32 v36, v36, v40
	v_add_f32_e32 v36, v36, v41
	v_add_f32_e32 v36, v36, v42
	v_add_f32_e32 v36, v36, v43
	s_waitcnt vmcnt(0)
	v_add_f32_e32 v36, v36, v44
	global_store_dword v2, v36, s[24:25]
.Lmy_p0_tr:
	s_lshl_b32 s6, s2, 3
	s_add_u32 s6, s6, s3
	s_add_u32 s6, s6, 512
	s_and_b32 s7, s6, 0x7ff
	v_lshrrev_b32_e32 v7, 5, v3
	v_and_b32_e32 v8, 31, v3
	v_lshl_add_u32 v7, v7, 6, v8
.Lmy_p0_tile:
	s_mov_b32 s14, 0
	s_mov_b32 s26, 0
	s_mov_b32 s27, 0
	s_mov_b32 s13, 0x800
	s_cmp_lt_u32 s7, 384
	s_cbranch_scc0 .Lmy_p0_cB
	s_movk_i32 s20, 0x68
	s_movk_i32 s21, 0xd0
	s_mov_b32 s12, 0x1800
	s_mul_hi_u32 s15, s7, 0xaaaaaab
	s_mul_i32 s16, s15, 24
	s_sub_u32 s16, s7, s16
	s_branch .Lmy_p0_dec
.Lmy_p0_cB:
	s_cmp_lt_u32 s7, 640
	s_cbranch_scc0 .Lmy_p0_cC
	s_sub_u32 s72, s7, 384
	s_movk_i32 s20, 0xa8
	s_movk_i32 s21, 0xd8
	s_mov_b32 s12, 0x1000
	s_lshr_b32 s15, s72, 4
	s_and_b32 s16, s72, 15
	s_branch .Lmy_p0_dec
.Lmy_p0_cC:
	s_cmp_lt_u32 s7, 1408
	s_cbranch_scc0 .Lmy_p0_cD
	s_sub_u32 s72, s7, 640
	s_movk_i32 s20, 0xb0
	s_movk_i32 s21, 0xe0
	s_mov_b32 s12, 0x3000
	s_mul_hi_u32 s15, s72, 0x5555556
	s_mul_i32 s16, s15, 48
	s_sub_u32 s16, s72, s16
	s_branch .Lmy_p0_dec
.Lmy_p0_cD:
	s_cmp_lt_u32 s7, 1664
	s_cbranch_scc0 .Lmy_p0_cE
	s_sub_u32 s72, s7, 1408
	s_movk_i32 s20, 0xc0
	s_movk_i32 s21, 0xe8
	s_mov_b32 s12, 0x1000
	s_lshr_b32 s15, s72, 4
	s_and_b32 s16, s72, 15
	s_branch .Lmy_p0_dec
.Lmy_p0_cE:
	s_cmp_lt_u32 s7, 4480
	s_cbranch_scc0 .Lmy_p0_cF
	s_sub_u32 s72, s7, 1664
	s_mul_hi_u32 s73, s72, 0x5d1746
	s_mul_i32 s74, s73, 704
	s_sub_u32 s74, s72, s74
	s_and_b32 s75, s73, 1
	s_lshr_b32 s76, s73, 1
	s_lshl_b32 s20, s76, 3
	s_add_u32 s20, s20, 0x50
	s_add_u32 s14, s76, 1
	s_mul_i32 s26, s75, 0xb00000
	s_mul_i32 s27, s75, 0xb00000
	s_movk_i32 s21, 0xf0
	s_mov_b32 s12, 0x2c00
	s_mul_hi_u32 s15, s74, 0x5d1745e
	s_mul_i32 s16, s15, 44
	s_sub_u32 s16, s74, s16
	s_branch .Lmy_p0_dec
.Lmy_p0_cF:
	s_sub_u32 s72, s7, 4480
	s_mul_hi_u32 s75, s72, 0x5d1746
	s_mul_i32 s74, s75, 704
	s_sub_u32 s74, s72, s74
	s_mul_i32 s26, s75, 0xb00000
	s_mul_i32 s27, s75, 0x580000
	s_movk_i32 s20, 0x60
	s_movk_i32 s21, 0xf8
	s_mov_b32 s12, 0x1000
	s_mov_b32 s13, 0x1600
	s_lshr_b32 s15, s74, 4
	s_and_b32 s16, s74, 15
; __device__ __forceinline__ void transpose_tile(const float* src, int ldn, int k0, int n0, u16* dst, int ldk, int mode, float* sm) {
;   const int tid = VTID;
;   const int cc = tid & 63, rr = tid >> 6;
; #pragma unroll 4
;   for (int i = 0; i < 16; ++i) {
;     const int r = rr + 4 * i;
;     sm[r * 65 + cc] = src[(long)(k0 + r) * ldn + n0 + cc];
;   }
;   __syncthreads();
; #pragma unroll
;   for (int i = 0; i < 2; ++i) {
;     const int n = (tid >> 3) + 32 * i, kg = tid & 7;
;     unsigned v[8];
; #pragma unroll
;     for (int j = 0; j < 8; ++j) v[j] = f2bf(sm[(kg * 8 + j) * 65 + n]);
;     const int gn = n0 + n;
;     int drow = gn;
;     if (mode == 1) drow = (gn >> 5) * 64 + (gn & 31);
;     else if (mode == 2) drow = (gn >> 5) * 64 + 32 + (gn & 31);
;     *reinterpret_cast<uint4*>(&dst[(long)drow * ldk + k0 + kg * 8]) =
;         make_uint4(v[0] | (v[1] << 16), v[2] | (v[3] << 16), v[4] | (v[5] << 16), v[6] | (v[7] << 16));
;   }
; __device__ __forceinline__ void prep_phase(const Params& P, float* sm) {
;     ...
;       src = (isup ? P.w_up : P.w_gate) + (long)l * 1024 * 2816;
;       dst = P.wt_gu + (long)l * 5632 * 1024;
;       ldn = 2816; ldk = 1024; mode = isup ? 2 : 1; kt = tq / 44; ntl = tq % 44;
;     } else {
;       t -= 1664 + 2816;
;       const int l = t / 704, tq = t % 704;
;       src = P.w_down + (long)l * 2816 * 1024;
;       dst = P.wt_dn + (long)l * 1024 * 2816;
;       ldn = 1024; ldk = 2816; kt = tq / 16; ntl = tq % 16;
;     }
.Lmy_p0_dec:
	s_load_dwordx2 s[8:9], s[4:5], s20
	s_load_dwordx2 s[10:11], s[4:5], s21
	s_lshl_b32 s72, s15, 6
	s_mul_i32 s72, s72, s12
	s_lshl_b32 s73, s16, 8
	s_add_u32 s72, s72, s73
	s_add_u32 s72, s72, s26
	s_lshl_b32 s73, s16, 6
	s_lshl_b32 s74, s16, 7
	s_cmp_eq_u32 s14, 2
	s_cselect_b32 s75, 32, 0
	s_add_u32 s74, s74, s75
	s_cmp_eq_u32 s14, 0
	s_cselect_b32 s73, s73, s74
	s_cselect_b64 s[76:77], -1, 0
	s_mul_i32 s73, s73, s13
	s_lshl_b32 s74, s15, 7
	s_add_u32 s73, s73, s74
	s_add_u32 s73, s73, s27
	v_cndmask_b32_e64 v9, v7, v3, s[76:77]
	v_mul_u32_u24_e32 v9, s13, v9
	s_waitcnt vmcnt(0)
	s_waitcnt lgkmcnt(0)
	s_add_u32 s8, s8, s72
	s_addc_u32 s9, s9, 0
	s_add_u32 s10, s10, s73
	s_addc_u32 s11, s11, 0
	global_load_dword v64, v2, s[8:9]
	s_add_u32 s8, s8, s12
	s_addc_u32 s9, s9, 0
	global_load_dword v65, v2, s[8:9]
	s_add_u32 s8, s8, s12
	s_addc_u32 s9, s9, 0
	global_load_dword v66, v2, s[8:9]
	s_add_u32 s8, s8, s12
	s_addc_u32 s9, s9, 0
	global_load_dword v67, v2, s[8:9]
	s_add_u32 s8, s8, s12
	s_addc_u32 s9, s9, 0
	global_load_dword v68, v2, s[8:9]
	s_add_u32 s8, s8, s12
	s_addc_u32 s9, s9, 0
	global_load_dword v69, v2, s[8:9]
	s_add_u32 s8, s8, s12
	s_addc_u32 s9, s9, 0
	global_load_dword v70, v2, s[8:9]
	s_add_u32 s8, s8, s12
	s_addc_u32 s9, s9, 0
	global_load_dword v71, v2, s[8:9]
	s_add_u32 s8, s8, s12
	s_addc_u32 s9, s9, 0
	global_load_dword v72, v2, s[8:9]
	s_add_u32 s8, s8, s12
	s_addc_u32 s9, s9, 0
	global_load_dword v73, v2, s[8:9]
	s_add_u32 s8, s8, s12
	s_addc_u32 s9, s9, 0
	global_load_dword v74, v2, s[8:9]
	s_add_u32 s8, s8, s12
	s_addc_u32 s9, s9, 0
	global_load_dword v75, v2, s[8:9]
	s_add_u32 s8, s8, s12
	s_addc_u32 s9, s9, 0
	global_load_dword v76, v2, s[8:9]
	s_add_u32 s8, s8, s12
	s_addc_u32 s9, s9, 0
	global_load_dword v77, v2, s[8:9]
	s_add_u32 s8, s8, s12
	s_addc_u32 s9, s9, 0
	global_load_dword v78, v2, s[8:9]
	s_add_u32 s8, s8, s12
	s_addc_u32 s9, s9, 0
	global_load_dword v79, v2, s[8:9]
	s_add_u32 s8, s8, s12
	s_addc_u32 s9, s9, 0
	global_load_dword v80, v2, s[8:9]
	s_add_u32 s8, s8, s12
	s_addc_u32 s9, s9, 0
	global_load_dword v81, v2, s[8:9]
	s_add_u32 s8, s8, s12
	s_addc_u32 s9, s9, 0
	global_load_dword v82, v2, s[8:9]
	s_add_u32 s8, s8, s12
	s_addc_u32 s9, s9, 0
	global_load_dword v83, v2, s[8:9]
	s_add_u32 s8, s8, s12
	s_addc_u32 s9, s9, 0
	global_load_dword v84, v2, s[8:9]
	s_add_u32 s8, s8, s12
	s_addc_u32 s9, s9, 0
	global_load_dword v85, v2, s[8:9]
	s_add_u32 s8, s8, s12
	s_addc_u32 s9, s9, 0
	global_load_dword v86, v2, s[8:9]
	s_add_u32 s8, s8, s12
	s_addc_u32 s9, s9, 0
	global_load_dword v87, v2, s[8:9]
	s_add_u32 s8, s8, s12
	s_addc_u32 s9, s9, 0
	global_load_dword v88, v2, s[8:9]
	s_add_u32 s8, s8, s12
	s_addc_u32 s9, s9, 0
	global_load_dword v89, v2, s[8:9]
	s_add_u32 s8, s8, s12
	s_addc_u32 s9, s9, 0
	global_load_dword v90, v2, s[8:9]
	s_add_u32 s8, s8, s12
	s_addc_u32 s9, s9, 0
	global_load_dword v91, v2, s[8:9]
	s_add_u32 s8, s8, s12
	s_addc_u32 s9, s9, 0
	global_load_dword v92, v2, s[8:9]
	s_add_u32 s8, s8, s12
	s_addc_u32 s9, s9, 0
	global_load_dword v93, v2, s[8:9]
	s_add_u32 s8, s8, s12
	s_addc_u32 s9, s9, 0
	global_load_dword v94, v2, s[8:9]
	s_add_u32 s8, s8, s12
	s_addc_u32 s9, s9, 0
	global_load_dword v95, v2, s[8:9]
	s_add_u32 s8, s8, s12
	s_addc_u32 s9, s9, 0
	global_load_dword v96, v2, s[8:9]
	s_add_u32 s8, s8, s12
	s_addc_u32 s9, s9, 0
	global_load_dword v97, v2, s[8:9]
	s_add_u32 s8, s8, s12
	s_addc_u32 s9, s9, 0
	global_load_dword v98, v2, s[8:9]
	s_add_u32 s8, s8, s12
	s_addc_u32 s9, s9, 0
	global_load_dword v99, v2, s[8:9]
	s_add_u32 s8, s8, s12
	s_addc_u32 s9, s9, 0
	global_load_dword v100, v2, s[8:9]
	s_add_u32 s8, s8, s12
	s_addc_u32 s9, s9, 0
	global_load_dword v101, v2, s[8:9]
	s_add_u32 s8, s8, s12
	s_addc_u32 s9, s9, 0
	global_load_dword v102, v2, s[8:9]
	s_add_u32 s8, s8, s12
	s_addc_u32 s9, s9, 0
	global_load_dword v103, v2, s[8:9]
	s_add_u32 s8, s8, s12
	s_addc_u32 s9, s9, 0
	global_load_dword v104, v2, s[8:9]
	s_add_u32 s8, s8, s12
	s_addc_u32 s9, s9, 0
	global_load_dword v105, v2, s[8:9]
	s_add_u32 s8, s8, s12
	s_addc_u32 s9, s9, 0
	global_load_dword v106, v2, s[8:9]
	s_add_u32 s8, s8, s12
	s_addc_u32 s9, s9, 0
	global_load_dword v107, v2, s[8:9]
	s_add_u32 s8, s8, s12
	s_addc_u32 s9, s9, 0
	global_load_dword v108, v2, s[8:9]
	s_add_u32 s8, s8, s12
	s_addc_u32 s9, s9, 0
	global_load_dword v109, v2, s[8:9]
	s_add_u32 s8, s8, s12
	s_addc_u32 s9, s9, 0
	global_load_dword v110, v2, s[8:9]
	s_add_u32 s8, s8, s12
	s_addc_u32 s9, s9, 0
	global_load_dword v111, v2, s[8:9]
	s_add_u32 s8, s8, s12
	s_addc_u32 s9, s9, 0
	global_load_dword v112, v2, s[8:9]
	s_add_u32 s8, s8, s12
	s_addc_u32 s9, s9, 0
	global_load_dword v113, v2, s[8:9]
	s_add_u32 s8, s8, s12
	s_addc_u32 s9, s9, 0
	global_load_dword v114, v2, s[8:9]
	s_add_u32 s8, s8, s12
	s_addc_u32 s9, s9, 0
	global_load_dword v115, v2, s[8:9]
	s_add_u32 s8, s8, s12
	s_addc_u32 s9, s9, 0
	global_load_dword v116, v2, s[8:9]
	s_add_u32 s8, s8, s12
	s_addc_u32 s9, s9, 0
	global_load_dword v117, v2, s[8:9]
	s_add_u32 s8, s8, s12
	s_addc_u32 s9, s9, 0
	global_load_dword v118, v2, s[8:9]
	s_add_u32 s8, s8, s12
	s_addc_u32 s9, s9, 0
	global_load_dword v119, v2, s[8:9]
	s_add_u32 s8, s8, s12
	s_addc_u32 s9, s9, 0
	global_load_dword v120, v2, s[8:9]
	s_add_u32 s8, s8, s12
	s_addc_u32 s9, s9, 0
	global_load_dword v121, v2, s[8:9]
	s_add_u32 s8, s8, s12
	s_addc_u32 s9, s9, 0
	global_load_dword v122, v2, s[8:9]
	s_add_u32 s8, s8, s12
	s_addc_u32 s9, s9, 0
	global_load_dword v123, v2, s[8:9]
	s_add_u32 s8, s8, s12
	s_addc_u32 s9, s9, 0
	global_load_dword v124, v2, s[8:9]
	s_add_u32 s8, s8, s12
	s_addc_u32 s9, s9, 0
	global_load_dword v125, v2, s[8:9]
	s_add_u32 s8, s8, s12
	s_addc_u32 s9, s9, 0
	s_waitcnt vmcnt(60)
; __device__ __forceinline__ void transpose_tile(const float* src, int ldn, int k0, int n0, u16* dst, int ldk, int mode, float* sm) {
;     ...
;   for (int i = 0; i < 2; ++i) {
;     const int n = (tid >> 3) + 32 * i, kg = tid & 7;
;     unsigned v[8];
; #pragma unroll
;     for (int j = 0; j < 8; ++j) v[j] = f2bf(sm[(kg * 8 + j) * 65 + n]);
;     const int gn = n0 + n;
;     int drow = gn;
;     if (mode == 1) drow = (gn >> 5) * 64 + (gn & 31);
;     else if (mode == 2) drow = (gn >> 5) * 64 + 32 + (gn & 31);
;     *reinterpret_cast<uint4*>(&dst[(long)drow * ldk + k0 + kg * 8]) =
;         make_uint4(v[0] | (v[1] << 16), v[2] | (v[3] << 16), v[4] | (v[5] << 16), v[6] | (v[7] << 16));
;   }
	global_load_dword v126, v2, s[8:9]
	s_add_u32 s8, s8, s12
	s_addc_u32 s9, s9, 0
	global_load_dword v127, v2, s[8:9]
	s_waitcnt vmcnt(56)
	v_cvt_pk_bf16_f32 v64, v64, v65
	v_cvt_pk_bf16_f32 v65, v66, v67
	v_cvt_pk_bf16_f32 v66, v68, v69
	v_cvt_pk_bf16_f32 v67, v70, v71
	s_waitcnt vmcnt(48)
	v_cvt_pk_bf16_f32 v68, v72, v73
	v_cvt_pk_bf16_f32 v69, v74, v75
	v_cvt_pk_bf16_f32 v70, v76, v77
	v_cvt_pk_bf16_f32 v71, v78, v79
	s_waitcnt vmcnt(40)
	v_cvt_pk_bf16_f32 v72, v80, v81
	v_cvt_pk_bf16_f32 v73, v82, v83
	v_cvt_pk_bf16_f32 v74, v84, v85
	v_cvt_pk_bf16_f32 v75, v86, v87
	s_waitcnt vmcnt(32)
	v_cvt_pk_bf16_f32 v76, v88, v89
	v_cvt_pk_bf16_f32 v77, v90, v91
	v_cvt_pk_bf16_f32 v78, v92, v93
	v_cvt_pk_bf16_f32 v79, v94, v95
	s_waitcnt vmcnt(24)
	v_cvt_pk_bf16_f32 v80, v96, v97
	v_cvt_pk_bf16_f32 v81, v98, v99
	v_cvt_pk_bf16_f32 v82, v100, v101
	v_cvt_pk_bf16_f32 v83, v102, v103
	s_waitcnt vmcnt(16)
	v_cvt_pk_bf16_f32 v84, v104, v105
	v_cvt_pk_bf16_f32 v85, v106, v107
	v_cvt_pk_bf16_f32 v86, v108, v109
	v_cvt_pk_bf16_f32 v87, v110, v111
	s_waitcnt vmcnt(8)
	v_cvt_pk_bf16_f32 v88, v112, v113
	v_cvt_pk_bf16_f32 v89, v114, v115
	v_cvt_pk_bf16_f32 v90, v116, v117
	v_cvt_pk_bf16_f32 v91, v118, v119
	s_waitcnt vmcnt(0)
	v_cvt_pk_bf16_f32 v92, v120, v121
	v_cvt_pk_bf16_f32 v93, v122, v123
	v_cvt_pk_bf16_f32 v94, v124, v125
	v_cvt_pk_bf16_f32 v95, v126, v127
	global_store_dwordx4 v9, v[64:67], s[10:11] offset:0
	global_store_dwordx4 v9, v[68:71], s[10:11] offset:16
	global_store_dwordx4 v9, v[72:75], s[10:11] offset:32
	global_store_dwordx4 v9, v[76:79], s[10:11] offset:48
	global_store_dwordx4 v9, v[80:83], s[10:11] offset:64
	global_store_dwordx4 v9, v[84:87], s[10:11] offset:80
	global_store_dwordx4 v9, v[88:91], s[10:11] offset:96
	global_store_dwordx4 v9, v[92:95], s[10:11] offset:112
	s_add_u32 s7, s7, 0x800
	s_cmp_lt_u32 s7, 5888
	s_cbranch_scc1 .Lmy_p0_tile
	s_mov_b64 s[0:1], 0
	s_mov_b64 s[34:35], s[96:97]
	v_readlane_b32 s96, v252, 52
	v_readlane_b32 s97, v252, 53
